# P0 main loop: LN / row-max butterfly steps and gate-reduce lane^8,^2,^1 moves via DPP and permlane swaps instead of ds_bpermute (44 of 70 per iteration), bit-identical
# baseline (speedup 1.0000x reference)
.LBB0_61:
	global_load_dwordx4 v[20:23], v[114:115], off offset:-2048 nt
	global_load_dwordx4 v[24:27], v[114:115], off offset:-4096 nt
	global_load_dwordx4 v[28:31], v[114:115], off offset:-3072 nt
	global_load_dwordx4 v[36:39], v[114:115], off offset:-1024 nt
	global_load_dwordx4 v[2:5], v[114:115], off offset:3072 nt
	global_load_dwordx4 v[10:13], v[114:115], off offset:2048 nt
	global_load_dwordx4 v[14:17], v[114:115], off offset:1024 nt
	global_load_dwordx4 v[32:35], v[114:115], off nt
	v_add_u32_e32 v232, s51, v90
	v_cmp_gt_i32_e64 s[16:17], s45, v232
	v_lshl_add_u64 v[76:77], s[80:81], 0, v[112:113]
	s_waitcnt vmcnt(7)
	v_mov_b32_e32 v6, v21
	s_waitcnt vmcnt(6)
	v_mov_b32_e32 v8, v24
	s_waitcnt vmcnt(5)
	v_mov_b32_e32 v9, v28
	v_mov_b32_e32 v18, v25
	v_mov_b32_e32 v19, v29
	v_mov_b32_e32 v40, v26
	v_mov_b32_e32 v41, v30
	v_mov_b32_e32 v42, v27
	v_mov_b32_e32 v43, v31
	v_mov_b32_e32 v7, v22
	v_mov_b32_e32 v44, v20
	v_mov_b32_e32 v45, v23
	v_pk_add_f32 v[8:9], v[8:9], v[18:19]
	v_pk_add_f32 v[18:19], v[40:41], v[42:43]
	s_waitcnt vmcnt(4)
	v_mov_b32_e32 v46, v37
	v_mov_b32_e32 v48, v39
	s_waitcnt vmcnt(0)
	v_mov_b32_e32 v47, v32
	v_pk_add_f32 v[6:7], v[6:7], v[44:45]
	v_pk_add_f32 v[8:9], v[8:9], v[18:19]
	v_pk_add_f32 v[40:41], v[36:37], v[46:47]
	v_pk_add_f32 v[42:43], v[38:39], v[48:49]
	v_pk_add_f32 v[6:7], v[6:7], v[6:7] op_sel:[0,1] op_sel_hi:[1,0]
	v_add_f32_e32 v8, 0, v8
	v_mov_b32_e32 v41, v34
	v_mov_b32_e32 v43, v35
	v_mov_b32_e32 v7, v33
	v_add_f32_e32 v46, v8, v9
	v_mov_b32_e32 v56, v16
	v_mov_b32_e32 v50, v14
	v_mov_b32_e32 v51, v16
	v_mov_b32_e32 v16, v15
	v_pk_add_f32 v[40:41], v[40:41], v[42:43]
	v_pk_add_f32 v[6:7], v[46:47], v[6:7]
	v_mov_b32_e32 v52, v2
	v_mov_b32_e32 v53, v10
	v_mov_b32_e32 v54, v4
	v_mov_b32_e32 v55, v12
	v_pk_add_f32 v[48:49], v[50:51], v[16:17]
	v_pk_add_f32 v[6:7], v[6:7], v[40:41]
	v_mov_b32_e32 v4, v5
	v_mov_b32_e32 v5, v13
	v_pk_add_f32 v[44:45], v[52:53], v[10:11]
	v_pk_add_f32 v[12:13], v[54:55], v[12:13]
	v_pk_add_f32 v[18:19], v[48:49], v[48:49] op_sel:[0,1] op_sel_hi:[1,0]
	v_pk_add_f32 v[6:7], v[6:7], v[6:7] op_sel:[0,1] op_sel_hi:[1,0]
	v_pk_mov_b32 v[44:45], v[44:45], v[54:55] op_sel:[1,0]
	v_pk_mov_b32 v[12:13], v[12:13], v[4:5] op_sel:[1,0]
	v_mov_b32_e32 v19, v3
	v_mov_b32_e32 v7, v2
	v_pk_add_f32 v[12:13], v[44:45], v[12:13]
	v_pk_add_f32 v[6:7], v[6:7], v[18:19]
	v_mov_b32_e32 v57, v34
	v_pk_add_f32 v[6:7], v[6:7], v[12:13]
	s_nop 0
	v_add_f32_e32 v2, v6, v7
	v_mov_b32_e32 v6, v2
	s_nop 1
	v_permlane32_swap_b32 v6, v2
	s_waitcnt lgkmcnt(0)
	v_add_f32_e32 v2, v2, v6
	v_mov_b32_e32 v6, v2
	s_nop 1
	v_permlane16_swap_b32 v6, v2
	s_waitcnt lgkmcnt(0)
	v_add_f32_e32 v2, v2, v6
	s_nop 1
	v_mov_b32_dpp v6, v2 row_ror:8 row_mask:0xf bank_mask:0xf
	s_waitcnt lgkmcnt(0)
	v_add_f32_e32 v10, v2, v6
	ds_read_b128 v[44:47], v102 offset:0
	ds_read_b128 v[6:9], v102 offset:8192
	s_nop 1
	v_mov_b32_dpp v12, v10 row_ror:12 row_mask:0xf bank_mask:0x5
	v_mov_b32_dpp v12, v10 row_ror:4 row_mask:0xf bank_mask:0xa
	v_mov_b32_e32 v2, v3
	v_mov_b32_e32 v3, v11
	v_mov_b32_e32 v11, v32
	s_waitcnt lgkmcnt(0)
	v_add_f32_e32 v13, v10, v12
	s_nop 1
	v_mov_b32_dpp v16, v13 quad_perm:[2,3,0,1] row_mask:0xf bank_mask:0xf
	v_mov_b32_e32 v10, v14
	v_mov_b32_e32 v14, v17
	v_mov_b32_e32 v12, v15
	v_mov_b32_e32 v15, v35
	s_waitcnt lgkmcnt(0)
	v_add_f32_e32 v16, v13, v16
	s_nop 1
	v_mov_b32_dpp v18, v16 quad_perm:[1,0,3,2] row_mask:0xf bank_mask:0xf
	v_mov_b32_e32 v13, v33
	s_waitcnt lgkmcnt(0)
	v_add_f32_e32 v17, v16, v18
	v_fmamk_f32 v33, v17, 0xba000000, v25
	v_fmamk_f32 v41, v17, 0xba000000, v29
	v_mul_f32_e32 v16, 0x3a000000, v17
	v_fmamk_f32 v32, v17, 0xba000000, v24
	v_fmamk_f32 v26, v17, 0xba000000, v26
	v_fmac_f32_e32 v27, 0xba000000, v17
	v_fmamk_f32 v40, v17, 0xba000000, v28
	v_fmamk_f32 v30, v17, 0xba000000, v30
	v_fmac_f32_e32 v31, 0xba000000, v17
	v_fmamk_f32 v80, v17, 0xba000000, v20
	v_fmamk_f32 v81, v17, 0xba000000, v21
	v_fmamk_f32 v22, v17, 0xba000000, v22
	v_fmac_f32_e32 v23, 0xba000000, v17
	v_fmamk_f32 v82, v17, 0xba000000, v36
	v_fmamk_f32 v83, v17, 0xba000000, v37
	v_fmamk_f32 v38, v17, 0xba000000, v38
	v_fmac_f32_e32 v39, 0xba000000, v17
	v_mul_f32_e32 v17, v33, v33
	v_mul_f32_e32 v18, v41, v41
	v_mul_f32_e32 v19, v81, v81
	v_pk_add_f32 v[48:49], v[10:11], v[16:17] op_sel_hi:[1,0] neg_lo:[0,1] neg_hi:[0,1]
	v_pk_add_f32 v[50:51], v[12:13], v[16:17] op_sel_hi:[1,0] neg_lo:[0,1] neg_hi:[0,1]
	v_pk_add_f32 v[56:57], v[56:57], v[16:17] op_sel_hi:[1,0] neg_lo:[0,1] neg_hi:[0,1]
	v_pk_add_f32 v[78:79], v[14:15], v[16:17] op_sel_hi:[1,0] neg_lo:[0,1] neg_hi:[0,1]
	v_pk_add_f32 v[42:43], v[52:53], v[16:17] op_sel_hi:[1,0] neg_lo:[0,1] neg_hi:[0,1]
	v_pk_add_f32 v[70:71], v[2:3], v[16:17] op_sel_hi:[1,0] neg_lo:[0,1] neg_hi:[0,1]
	v_pk_add_f32 v[72:73], v[54:55], v[16:17] op_sel_hi:[1,0] neg_lo:[0,1] neg_hi:[0,1]
	v_pk_add_f32 v[74:75], v[4:5], v[16:17] op_sel_hi:[1,0] neg_lo:[0,1] neg_hi:[0,1]
	v_fmac_f32_e32 v17, v32, v32
	v_fmac_f32_e32 v18, v40, v40
	v_mul_f32_e32 v20, v83, v83
	v_fmac_f32_e32 v19, v80, v80
	v_fmac_f32_e32 v17, v26, v26
	v_fmac_f32_e32 v18, v30, v30
	v_fmac_f32_e32 v20, v82, v82
	v_pk_mul_f32 v[2:3], v[50:51], v[50:51]
	v_fmac_f32_e32 v19, v22, v22
	v_fmac_f32_e32 v17, v27, v27
	v_fmac_f32_e32 v18, v31, v31
	v_fmac_f32_e32 v20, v38, v38
	v_pk_fma_f32 v[2:3], v[48:49], v[48:49], v[2:3]
	v_fmac_f32_e32 v19, v23, v23
	v_add_f32_e32 v10, v17, v18
	v_pk_mul_f32 v[4:5], v[70:71], v[70:71]
	v_fmac_f32_e32 v20, v39, v39
	v_pk_fma_f32 v[2:3], v[56:57], v[56:57], v[2:3]
	v_add_f32_e32 v10, v19, v10
	v_pk_fma_f32 v[4:5], v[42:43], v[42:43], v[4:5]
	v_pk_fma_f32 v[2:3], v[78:79], v[78:79], v[2:3]
	v_add_f32_e32 v10, v20, v10
	v_pk_fma_f32 v[4:5], v[72:73], v[72:73], v[4:5]
	v_add_f32_e32 v3, v3, v10
	v_pk_fma_f32 v[4:5], v[74:75], v[74:75], v[4:5]
	v_add_f32_e32 v2, v2, v3
	v_add_f32_e32 v2, v5, v2
	v_add_f32_e32 v2, v4, v2
	v_mov_b32_e32 v3, v2
	s_nop 1
	v_permlane32_swap_b32 v3, v2
	v_cndmask_b32_e64 v24, v90, v232, s[16:17]
	v_ashrrev_i32_e32 v25, 31, v24
	s_waitcnt lgkmcnt(0)
	v_add_f32_e32 v2, v2, v3
	v_mov_b32_e32 v3, v2
	s_nop 1
	v_permlane16_swap_b32 v3, v2
	s_waitcnt lgkmcnt(0)
	v_add_f32_e32 v2, v2, v3
	s_nop 1
	v_mov_b32_dpp v3, v2 row_ror:8 row_mask:0xf bank_mask:0xf
	s_waitcnt lgkmcnt(0)
	v_add_f32_e32 v4, v2, v3
	s_nop 1
	v_mov_b32_dpp v5, v4 row_ror:12 row_mask:0xf bank_mask:0x5
	v_mov_b32_dpp v5, v4 row_ror:4 row_mask:0xf bank_mask:0xa
	v_lshlrev_b64 v[2:3], 13, v[24:25]
	v_lshl_add_u64 v[28:29], v[100:101], 0, v[2:3]
	v_lshlrev_b64 v[24:25], 12, v[24:25]
	v_lshl_add_u64 v[24:25], v[118:119], 0, v[24:25]
	s_waitcnt lgkmcnt(0)
	v_add_f32_e32 v34, v4, v5
	s_nop 1
	v_mov_b32_dpp v35, v34 quad_perm:[2,3,0,1] row_mask:0xf bank_mask:0xf
	global_load_dwordx4 v[10:13], v[28:29], off offset:2048 nt
	global_load_dwordx4 v[2:5], v[28:29], off offset:3072 nt
	global_load_dwordx4 v[18:21], v[28:29], off nt
	global_load_dwordx4 v[14:17], v[28:29], off offset:1024 nt
	v_add_co_u32_e32 v28, vcc, s61, v28
	s_waitcnt lgkmcnt(0)
	v_add_f32_e32 v34, v34, v35
	s_nop 1
	v_mov_b32_dpp v35, v34 quad_perm:[1,0,3,2] row_mask:0xf bank_mask:0xf
	v_addc_co_u32_e32 v29, vcc, 0, v29, vcc
	global_load_dwordx4 v[52:55], v[28:29], off offset:2048 nt
	global_load_dwordx4 v[58:61], v[28:29], off offset:3072 nt
	global_load_dwordx4 v[62:65], v[28:29], off nt
	global_load_dwordx4 v[66:69], v[28:29], off offset:1024 nt
	s_waitcnt lgkmcnt(0)
	v_add_f32_e32 v34, v34, v35
	v_fmamk_f32 v34, v34, 0x3a000000, v228
	v_mul_f32_e32 v35, 0x4b800000, v34
	v_cmp_gt_f32_e32 vcc, s29, v34
	s_waitcnt vmcnt(3)
	s_waitcnt lgkmcnt(0)
	v_mov_b32_e32 v175, v55
	v_cndmask_b32_e32 v34, v34, v35, vcc
	v_rsq_f32_e32 v34, v34
	s_waitcnt vmcnt(2)
	v_mov_b32_e32 v174, v61
	v_mov_b32_e32 v61, v54
	v_pk_add_f32 v[176:177], v[60:61], v[54:55]
	v_mul_f32_e32 v28, 0x45800000, v34
	v_cndmask_b32_e32 v92, v34, v28, vcc
	v_mul_f32_e32 v28, v32, v92
	v_mul_f32_e32 v29, v33, v92
	v_mul_f32_e32 v26, v26, v92
	v_mul_f32_e32 v27, v27, v92
	v_fma_f32 v143, v46, v26, v8
	v_fma_f32 v141, v47, v27, v9
	v_fma_f32 v144, v44, v28, v6
	v_fmac_f32_e32 v7, v45, v29
	v_cvt_pk_bf16_f32 v8, v144, v7
	v_cvt_pk_bf16_f32 v9, v143, v141
	global_store_dwordx2 v[76:77], v[8:9], off nt
	ds_read_b128 v[26:29], v102 offset:9216
	ds_read_b128 v[32:35], v102 offset:1024
	v_mul_f32_e32 v6, v31, v92
	v_mul_f32_e32 v8, v40, v92
	v_mul_f32_e32 v9, v41, v92
	v_mul_f32_e32 v30, v30, v92
	v_mul_f32_e32 v22, v22, v92
	v_mov_b32_e32 v88, v58
	v_mov_b32_e32 v89, v52
	s_waitcnt vmcnt(2)
	v_mov_b32_e32 v87, v62
	v_pk_mov_b32 v[176:177], v[176:177], v[174:175] op_sel:[1,0]
	v_mul_f32_e32 v42, v42, v92
	s_waitcnt vmcnt(1)
	s_waitcnt lgkmcnt(0)
	v_fma_f32 v148, v32, v8, v26
	v_fma_f32 v151, v33, v9, v27
	v_fma_f32 v147, v34, v30, v28
	v_fmac_f32_e32 v29, v35, v6
	v_cvt_pk_bf16_f32 v8, v148, v151
	v_cvt_pk_bf16_f32 v9, v147, v29
	global_store_dwordx2 v[76:77], v[8:9], off offset:512 nt
	ds_read_b128 v[30:33], v102 offset:10240
	ds_read_b128 v[34:37], v102 offset:2048
	v_mul_f32_e32 v6, v23, v92
	v_mul_f32_e32 v8, v80, v92
	v_mul_f32_e32 v9, v81, v92
	v_mov_b32_e32 v23, v15
	v_mov_b32_e32 v26, v20
	v_mov_b32_e32 v27, v16
	v_mov_b32_e32 v28, v5
	v_pk_add_f32 v[84:85], v[4:5], v[28:29]
	v_mul_f32_e32 v28, v43, v92
	v_mov_b32_e32 v85, v65
	v_mul_f32_e32 v43, v70, v92
	s_waitcnt lgkmcnt(0)
	v_fmac_f32_e32 v33, v6, v37
	v_fma_f32 v152, v8, v34, v30
	v_fma_f32 v155, v9, v35, v31
	v_fma_f32 v31, v22, v36, v32
	v_cvt_pk_bf16_f32 v8, v152, v155
	v_cvt_pk_bf16_f32 v9, v31, v33
	global_store_dwordx2 v[76:77], v[8:9], off offset:1024 nt
	ds_read_b128 v[34:37], v102 offset:11264
	ds_read_b128 v[44:47], v102 offset:3072
	v_mul_f32_e32 v6, v39, v92
	v_mul_f32_e32 v8, v82, v92
	v_mul_f32_e32 v9, v83, v92
	v_mul_f32_e32 v22, v38, v92
	v_mul_f32_e32 v30, v71, v92
	v_mul_f32_e32 v32, v73, v92
	s_waitcnt lgkmcnt(0)
	v_fmac_f32_e32 v37, v6, v47
	v_fma_f32 v156, v8, v44, v34
	v_fma_f32 v159, v9, v45, v35
	v_fma_f32 v35, v22, v46, v36
	v_cvt_pk_bf16_f32 v8, v156, v159
	v_cvt_pk_bf16_f32 v9, v35, v37
	global_store_dwordx2 v[76:77], v[8:9], off offset:1536 nt
	ds_read_b128 v[38:41], v102 offset:12288
	ds_read_b128 v[44:47], v102 offset:4096
	v_mul_f32_e32 v6, v79, v92
	v_mul_f32_e32 v8, v49, v92
	v_mul_f32_e32 v9, v51, v92
	v_mul_f32_e32 v22, v57, v92
	v_mov_b32_e32 v57, v12
	s_waitcnt lgkmcnt(0)
	v_fmac_f32_e32 v41, v6, v47
	v_fma_f32 v160, v8, v44, v38
	v_fma_f32 v163, v9, v45, v39
	v_fma_f32 v39, v22, v46, v40
	v_cvt_pk_bf16_f32 v8, v160, v163
	v_cvt_pk_bf16_f32 v9, v39, v41
	global_store_dwordx2 v[76:77], v[8:9], off offset:2048 nt
	ds_read_b128 v[44:47], v102 offset:13312
	ds_read_b128 v[80:83], v102 offset:5120
	v_mul_f32_e32 v6, v48, v92
	v_mul_f32_e32 v8, v50, v92
	v_mul_f32_e32 v9, v56, v92
	v_mul_f32_e32 v22, v78, v92
	v_mov_b32_e32 v56, v11
	s_waitcnt lgkmcnt(0)
	v_fmac_f32_e32 v47, v22, v83
	v_fma_f32 v166, v6, v80, v44
	v_fma_f32 v169, v8, v81, v45
	v_fma_f32 v165, v9, v82, v46
	v_cvt_pk_bf16_f32 v8, v166, v169
	v_cvt_pk_bf16_f32 v9, v165, v47
	global_store_dwordx2 v[76:77], v[8:9], off offset:2560 nt
	ds_read_b128 v[48:51], v102 offset:14336
	ds_read_b128 v[78:81], v102 offset:6144
	v_mov_b32_e32 v8, v18
	v_mov_b32_e32 v9, v14
	v_mov_b32_e32 v22, v19
	v_mov_b32_e32 v44, v21
	v_mov_b32_e32 v45, v17
	v_pk_add_f32 v[8:9], v[8:9], v[22:23]
	v_pk_add_f32 v[22:23], v[26:27], v[44:45]
	v_mov_b32_e32 v82, v10
	v_mov_b32_e32 v83, v13
	v_mov_b32_e32 v6, v3
	v_pk_add_f32 v[8:9], v[8:9], v[22:23]
	v_pk_add_f32 v[26:27], v[56:57], v[82:83]
	v_pk_add_f32 v[56:57], v[2:3], v[6:7]
	v_add_f32_e32 v6, 0, v8
	v_mul_f32_e32 v8, v75, v92
	v_mov_b32_e32 v57, v64
	v_pk_add_f32 v[84:85], v[56:57], v[84:85]
	v_pk_add_f32 v[26:27], v[26:27], v[26:27] op_sel:[0,1] op_sel_hi:[1,0]
	v_pk_add_f32 v[22:23], v[88:89], v[52:53]
	v_mov_b32_e32 v27, v63
	v_pk_mov_b32 v[22:23], v[22:23], v[60:61] op_sel:[1,0]
	v_add_f32_e32 v86, v6, v9
	v_mov_b32_e32 v44, v66
	v_mov_b32_e32 v45, v68
	v_mov_b32_e32 v82, v68
	v_mov_b32_e32 v68, v67
	v_pk_add_f32 v[44:45], v[44:45], v[68:69]
	v_mov_b32_e32 v52, v59
	v_pk_add_f32 v[44:45], v[44:45], v[44:45] op_sel:[0,1] op_sel_hi:[1,0]
	v_mov_b32_e32 v83, v64
	v_mov_b32_e32 v45, v59
	s_waitcnt lgkmcnt(0)
	v_fmac_f32_e32 v51, v8, v81
	v_fma_f32 v170, v28, v78, v48
	v_fma_f32 v173, v30, v79, v49
	v_fma_f32 v49, v32, v80, v50
	v_cvt_pk_bf16_f32 v54, v170, v173
	v_cvt_pk_bf16_f32 v55, v49, v51
	global_store_dwordx2 v[76:77], v[54:55], off offset:3072 nt
	ds_read_b128 v[54:57], v102 offset:15360
	s_nop 0
	ds_read_b128 v[78:81], v102 offset:7168
	v_pk_add_f32 v[8:9], v[22:23], v[176:177]
	v_pk_add_f32 v[22:23], v[86:87], v[26:27]
	v_mul_f32_e32 v50, v72, v92
	v_pk_add_f32 v[22:23], v[22:23], v[84:85]
	s_waitcnt lgkmcnt(0)
	v_fma_f32 v176, v42, v78, v54
	v_pk_add_f32 v[22:23], v[22:23], v[22:23] op_sel:[0,1] op_sel_hi:[1,0]
	v_fma_f32 v179, v43, v79, v55
	v_mov_b32_e32 v23, v58
	v_pk_add_f32 v[22:23], v[22:23], v[44:45]
	v_cvt_pk_bf16_f32 v42, v176, v179
	s_nop 0
	v_pk_add_f32 v[8:9], v[22:23], v[8:9]
	v_mov_b32_e32 v22, v67
	v_add_f32_e32 v6, v8, v9
	v_mov_b32_e32 v8, v6
	s_nop 1
	v_permlane32_swap_b32 v8, v6
	v_mov_b32_e32 v23, v63
	v_mov_b32_e32 v67, v65
	s_waitcnt lgkmcnt(0)
	v_add_f32_e32 v6, v6, v8
	v_mov_b32_e32 v8, v6
	s_nop 1
	v_permlane16_swap_b32 v8, v6
	s_waitcnt lgkmcnt(0)
	v_add_f32_e32 v6, v6, v8
	s_nop 1
	v_mov_b32_dpp v8, v6 row_ror:8 row_mask:0xf bank_mask:0xf
	s_waitcnt lgkmcnt(0)
	v_add_f32_e32 v6, v6, v8
	s_nop 1
	v_mov_b32_dpp v9, v6 row_ror:12 row_mask:0xf bank_mask:0x5
	v_mov_b32_dpp v9, v6 row_ror:4 row_mask:0xf bank_mask:0xa
	v_mov_b32_e32 v8, v66
	v_mov_b32_e32 v66, v69
	s_waitcnt lgkmcnt(0)
	v_add_f32_e32 v6, v6, v9
	s_nop 1
	v_mov_b32_dpp v26, v6 quad_perm:[2,3,0,1] row_mask:0xf bank_mask:0xf
	v_mov_b32_e32 v9, v62
	s_waitcnt lgkmcnt(0)
	v_add_f32_e32 v6, v6, v26
	s_nop 1
	v_mov_b32_dpp v26, v6 quad_perm:[1,0,3,2] row_mask:0xf bank_mask:0xf
	s_waitcnt lgkmcnt(0)
	v_add_f32_e32 v26, v6, v26
	v_mul_f32_e32 v6, 0x3a000000, v26
	v_fmamk_f32 v34, v26, 0xba000000, v10
	v_fmamk_f32 v30, v26, 0xba000000, v11
	v_pk_add_f32 v[10:11], v[52:53], v[6:7] op_sel_hi:[1,0] neg_lo:[0,1] neg_hi:[0,1]
	v_mul_f32_e32 v52, v74, v92
	v_fmamk_f32 v32, v26, 0xba000000, v2
	v_fmamk_f32 v28, v26, 0xba000000, v3
	v_pk_add_f32 v[2:3], v[174:175], v[6:7] op_sel_hi:[1,0] neg_lo:[0,1] neg_hi:[0,1]
	v_fmac_f32_e32 v57, v52, v81
	v_fma_f32 v175, v50, v80, v56
	v_cvt_pk_bf16_f32 v43, v175, v57
	global_store_dwordx2 v[76:77], v[42:43], off offset:3584 nt
	v_pk_add_f32 v[44:45], v[8:9], v[6:7] op_sel_hi:[1,0] neg_lo:[0,1] neg_hi:[0,1]
	v_pk_add_f32 v[8:9], v[60:61], v[6:7] op_sel_hi:[1,0] neg_lo:[0,1] neg_hi:[0,1]
	ds_read_b128 v[52:55], v102 offset:0
	ds_read_b128 v[58:61], v102 offset:8192
	v_fmamk_f32 v48, v26, 0xba000000, v19
	v_fmamk_f32 v38, v26, 0xba000000, v15
	v_fmac_f32_e32 v21, 0xba000000, v26
	v_fmac_f32_e32 v17, 0xba000000, v26
	v_fmamk_f32 v46, v26, 0xba000000, v18
	v_fmamk_f32 v40, v26, 0xba000000, v14
	v_fmamk_f32 v20, v26, 0xba000000, v20
	v_fmamk_f32 v16, v26, 0xba000000, v16
	v_fmac_f32_e32 v13, 0xba000000, v26
	v_fmamk_f32 v12, v26, 0xba000000, v12
	v_fmac_f32_e32 v5, 0xba000000, v26
	v_fmamk_f32 v4, v26, 0xba000000, v4
	v_pk_add_f32 v[26:27], v[22:23], v[6:7] op_sel_hi:[1,0] neg_lo:[0,1] neg_hi:[0,1]
	v_pk_add_f32 v[22:23], v[82:83], v[6:7] op_sel_hi:[1,0] neg_lo:[0,1] neg_hi:[0,1]
	v_pk_add_f32 v[18:19], v[66:67], v[6:7] op_sel_hi:[1,0] neg_lo:[0,1] neg_hi:[0,1]
	v_pk_add_f32 v[14:15], v[88:89], v[6:7] op_sel_hi:[1,0] neg_lo:[0,1] neg_hi:[0,1]
	v_mul_f32_e32 v6, v48, v48
	v_mul_f32_e32 v36, v38, v38
	v_mul_f32_e32 v50, v30, v30
	v_fmac_f32_e32 v6, v46, v46
	v_fmac_f32_e32 v36, v40, v40
	v_mul_f32_e32 v56, v28, v28
	v_fmac_f32_e32 v50, v34, v34
	v_fmac_f32_e32 v6, v20, v20
	v_fmac_f32_e32 v36, v16, v16
	v_fmac_f32_e32 v56, v32, v32
	v_pk_mul_f32 v[42:43], v[26:27], v[26:27]
	v_fmac_f32_e32 v50, v12, v12
	v_fmac_f32_e32 v6, v21, v21
	v_fmac_f32_e32 v36, v17, v17
	v_fmac_f32_e32 v56, v4, v4
	v_pk_fma_f32 v[42:43], v[44:45], v[44:45], v[42:43]
	v_fmac_f32_e32 v50, v13, v13
	v_add_f32_e32 v6, v6, v36
	v_pk_mul_f32 v[62:63], v[10:11], v[10:11]
	v_fmac_f32_e32 v56, v5, v5
	v_pk_fma_f32 v[42:43], v[22:23], v[22:23], v[42:43]
	v_add_f32_e32 v6, v50, v6
	v_pk_fma_f32 v[62:63], v[14:15], v[14:15], v[62:63]
	v_pk_fma_f32 v[42:43], v[18:19], v[18:19], v[42:43]
	v_add_f32_e32 v6, v56, v6
	v_pk_fma_f32 v[62:63], v[8:9], v[8:9], v[62:63]
	v_add_f32_e32 v6, v43, v6
	v_pk_fma_f32 v[62:63], v[2:3], v[2:3], v[62:63]
	v_add_f32_e32 v6, v42, v6
	v_add_f32_e32 v6, v63, v6
	v_add_f32_e32 v6, v62, v6
	v_mov_b32_e32 v36, v6
	s_nop 1
	v_permlane32_swap_b32 v36, v6
	s_waitcnt lgkmcnt(0)
	v_add_f32_e32 v6, v6, v36
	v_mov_b32_e32 v36, v6
	s_nop 1
	v_permlane16_swap_b32 v36, v6
	s_waitcnt lgkmcnt(0)
	v_add_f32_e32 v6, v6, v36
	s_nop 1
	v_mov_b32_dpp v36, v6 row_ror:8 row_mask:0xf bank_mask:0xf
	s_waitcnt lgkmcnt(0)
	v_add_f32_e32 v6, v6, v36
	s_nop 1
	v_mov_b32_dpp v36, v6 row_ror:12 row_mask:0xf bank_mask:0x5
	v_mov_b32_dpp v36, v6 row_ror:4 row_mask:0xf bank_mask:0xa
	s_waitcnt lgkmcnt(0)
	v_add_f32_e32 v6, v6, v36
	s_nop 1
	v_mov_b32_dpp v36, v6 quad_perm:[2,3,0,1] row_mask:0xf bank_mask:0xf
	s_waitcnt lgkmcnt(0)
	v_add_f32_e32 v6, v6, v36
	s_nop 1
	v_mov_b32_dpp v36, v6 quad_perm:[1,0,3,2] row_mask:0xf bank_mask:0xf
	s_waitcnt lgkmcnt(0)
	v_add_f32_e32 v6, v6, v36
	v_fmamk_f32 v6, v6, 0x3a000000, v228
	v_mul_f32_e32 v36, 0x4b800000, v6
	v_cmp_gt_f32_e32 vcc, s29, v6
	s_nop 1
	v_cndmask_b32_e32 v6, v6, v36, vcc
	v_rsq_f32_e32 v6, v6
	s_nop 0
	v_mul_f32_e32 v36, 0x45800000, v6
	v_cndmask_b32_e32 v36, v6, v36, vcc
	v_mul_f32_e32 v21, v21, v36
	v_mul_f32_e32 v6, v46, v36
	v_mul_f32_e32 v42, v48, v36
	v_mul_f32_e32 v20, v20, v36
	s_waitcnt lgkmcnt(0)
	v_fma_f32 v6, v52, v6, v58
	v_fma_f32 v145, v53, v42, v59
	v_fma_f32 v142, v54, v20, v60
	v_fmac_f32_e32 v61, v55, v21
	v_cvt_pk_bf16_f32 v20, v6, v145
	v_cvt_pk_bf16_f32 v21, v142, v61
	s_and_saveexec_b64 s[0:1], s[16:17]
	s_cbranch_execz .LBB0_63
	global_store_dwordx2 v[24:25], v[20:21], off nt

.LBB0_77:
	s_or_b64 exec, exec, s[0:1]
	v_mov_b32_e32 v2, s55
	v_mov_b32_e32 v3, s57
	v_cmp_lt_i32_e64 s[18:19], s65, v90
	v_mov_b32_e32 v4, s56
	v_mov_b32_e32 v117, v93
	v_cndmask_b32_e64 v3, v2, v3, s[18:19]
	v_mov_b32_e32 v2, s54
	v_cndmask_b32_e64 v2, v2, v4, s[18:19]
	v_and_b32_e32 v4, 0x1fff800, v186
	v_lshlrev_b32_e32 v92, 2, v4
	v_lshl_add_u64 v[2:3], v[2:3], 0, v[92:93]
	v_lshl_add_u64 v[2:3], v[2:3], 0, v[116:117]
	global_load_dwordx4 v[20:23], v[2:3], off offset:48 nt
	global_load_dwordx4 v[24:27], v[2:3], off offset:32 nt
	global_load_dwordx4 v[42:45], v[2:3], off offset:16 nt
	global_load_dwordx4 v[52:55], v[2:3], off nt
	ds_read_b128 v[234:237], v1
	v_lshl_add_u64 v[12:13], v[2:3], 0, s[30:31]
	v_add_co_u32_e32 v2, vcc, s61, v2
	v_mov_b32_e32 v140, v61
	s_nop 0
	v_addc_co_u32_e32 v3, vcc, 0, v3, vcc
	global_load_dwordx4 v[16:19], v[2:3], off nt
	s_nop 0
	global_load_dwordx4 v[2:5], v[12:13], off offset:48 nt
	global_load_dwordx4 v[8:11], v[12:13], off offset:32 nt
	s_nop 0
	global_load_dwordx4 v[12:15], v[12:13], off offset:16 nt
	ds_read_b128 v[238:241], v1 offset:1024
	s_waitcnt lgkmcnt(1)
	v_pk_mul_f32 v[62:63], v[144:145], v[234:235]
	v_mov_b32_e32 v28, v237
	v_pk_fma_f32 v[62:63], v[6:7], v[234:235], v[62:63] op_sel:[0,0,1] op_sel_hi:[1,1,0]
	ds_read_b128 v[242:245], v1 offset:2048
	ds_read_b128 v[246:249], v1 offset:3072
	v_pk_fma_f32 v[62:63], v[142:143], v[236:237], v[62:63] op_sel_hi:[1,0,1]
	s_waitcnt lgkmcnt(2)
	v_mov_b32_e32 v32, v241
	v_pk_fma_f32 v[66:67], v[140:141], v[28:29], v[62:63] op_sel_hi:[1,0,1]
	v_pk_mul_f32 v[62:63], v[148:149], v[238:239]
	v_mov_b32_e32 v28, v65
	v_pk_fma_f32 v[62:63], v[150:151], v[238:239], v[62:63] op_sel:[0,0,1] op_sel_hi:[1,1,0]
	v_pk_add_f32 v[66:67], v[66:67], 0 op_sel_hi:[1,0]
	v_pk_fma_f32 v[70:71], v[146:147], v[240:241], v[62:63] op_sel_hi:[1,0,1]
	s_waitcnt lgkmcnt(1)
	v_mov_b32_e32 v36, v245
	v_pk_fma_f32 v[70:71], v[28:29], v[32:33], v[70:71] op_sel_hi:[1,0,1]
	v_mov_b32_e32 v32, v69
	v_pk_add_f32 v[66:67], v[66:67], v[70:71]
	v_pk_mul_f32 v[70:71], v[152:153], v[242:243]
	ds_read_b128 v[58:61], v1 offset:4096
	ds_read_b128 v[250:253], v1 offset:5120
	v_pk_fma_f32 v[70:71], v[154:155], v[242:243], v[70:71] op_sel:[0,0,1] op_sel_hi:[1,1,0]
	s_waitcnt lgkmcnt(2)
	v_mov_b32_e32 v40, v249
	v_pk_fma_f32 v[70:71], v[30:31], v[244:245], v[70:71] op_sel_hi:[1,0,1]
	ds_read_b128 v[62:65], v1 offset:6144
	ds_read_b128 v[234:237], v1 offset:7168
	v_pk_fma_f32 v[68:69], v[32:33], v[36:37], v[70:71] op_sel_hi:[1,0,1]
	v_mov_b32_e32 v36, v73
	v_pk_add_f32 v[66:67], v[66:67], v[68:69]
	v_pk_mul_f32 v[68:69], v[156:157], v[246:247]
	s_waitcnt lgkmcnt(3)
	v_mov_b32_e32 v46, v61
	v_pk_fma_f32 v[68:69], v[158:159], v[246:247], v[68:69] op_sel:[0,0,1] op_sel_hi:[1,1,0]
	s_waitcnt lgkmcnt(2)
	v_mov_b32_e32 v50, v253
	v_pk_fma_f32 v[68:69], v[34:35], v[248:249], v[68:69] op_sel_hi:[1,0,1]
	s_waitcnt lgkmcnt(1)
	v_mov_b32_e32 v56, v65
	v_pk_fma_f32 v[68:69], v[36:37], v[40:41], v[68:69] op_sel_hi:[1,0,1]
	v_mov_b32_e32 v40, v77
	v_pk_add_f32 v[66:67], v[66:67], v[68:69]
	v_pk_mul_f32 v[68:69], v[160:161], v[58:59]
	v_add_u32_e32 v92, 0x11000, v1
	v_pk_fma_f32 v[58:59], v[162:163], v[58:59], v[68:69] op_sel:[0,0,1] op_sel_hi:[1,1,0]
	v_cmp_gt_i32_e64 s[20:21], s64, v90
	v_pk_fma_f32 v[58:59], v[38:39], v[60:61], v[58:59] op_sel_hi:[1,0,1]
	v_pk_mul_f32 v[60:61], v[166:167], v[250:251]
	v_pk_fma_f32 v[58:59], v[40:41], v[46:47], v[58:59] op_sel_hi:[1,0,1]
	v_pk_fma_f32 v[60:61], v[168:169], v[250:251], v[60:61] op_sel:[0,0,1] op_sel_hi:[1,1,0]
	v_mov_b32_e32 v46, v81
	v_pk_fma_f32 v[60:61], v[164:165], v[252:253], v[60:61] op_sel_hi:[1,0,1]
	v_pk_add_f32 v[58:59], v[66:67], v[58:59]
	v_pk_fma_f32 v[60:61], v[46:47], v[50:51], v[60:61] op_sel_hi:[1,0,1]
	v_mov_b32_e32 v50, v85
	v_pk_add_f32 v[58:59], v[58:59], v[60:61]
	v_pk_mul_f32 v[60:61], v[170:171], v[62:63]
	s_waitcnt lgkmcnt(0)
	v_mov_b32_e32 v66, v237
	v_pk_fma_f32 v[60:61], v[172:173], v[62:63], v[60:61] op_sel:[0,0,1] op_sel_hi:[1,1,0]
	s_nop 0
	v_pk_fma_f32 v[60:61], v[48:49], v[64:65], v[60:61] op_sel_hi:[1,0,1]
	s_nop 0
	v_pk_fma_f32 v[60:61], v[50:51], v[56:57], v[60:61] op_sel_hi:[1,0,1]
	v_mov_b32_e32 v56, v89
	v_pk_add_f32 v[58:59], v[58:59], v[60:61]
	v_pk_mul_f32 v[60:61], v[176:177], v[234:235]
	s_nop 0
	v_pk_fma_f32 v[60:61], v[178:179], v[234:235], v[60:61] op_sel:[0,0,1] op_sel_hi:[1,1,0]
	s_nop 0
	v_pk_fma_f32 v[64:65], v[174:175], v[236:237], v[60:61] op_sel_hi:[1,0,1]
	ds_read_b128 v[60:63], v1 offset:8192
	v_pk_fma_f32 v[64:65], v[56:57], v[66:67], v[64:65] op_sel_hi:[1,0,1]
	s_nop 0
	v_pk_add_f32 v[58:59], v[58:59], v[64:65]
	ds_read_b128 v[64:67], v1 offset:9216
	s_waitcnt lgkmcnt(1)
	v_pk_mul_f32 v[88:89], v[144:145], v[60:61]
	ds_read_b128 v[68:71], v1 offset:10240
	ds_read_b128 v[72:75], v1 offset:11264
	ds_read_b128 v[76:79], v1 offset:12288
	ds_read_b128 v[80:83], v1 offset:13312
	ds_read_b128 v[84:87], v1 offset:14336
	ds_read_b128 v[234:237], v1 offset:15360
	v_pk_fma_f32 v[60:61], v[6:7], v[60:61], v[88:89] op_sel:[0,0,1] op_sel_hi:[1,1,0]
	s_nop 0
	v_pk_fma_f32 v[60:61], v[142:143], v[62:63], v[60:61] op_sel_hi:[1,0,1]
	v_mov_b32_e32 v62, v63
	v_pk_fma_f32 v[60:61], v[140:141], v[62:63], v[60:61] op_sel_hi:[1,0,1]
	s_waitcnt lgkmcnt(6)
	v_pk_mul_f32 v[62:63], v[148:149], v[64:65]
	v_pk_add_f32 v[60:61], v[60:61], 0 op_sel_hi:[1,0]
	v_pk_fma_f32 v[62:63], v[150:151], v[64:65], v[62:63] op_sel:[0,0,1] op_sel_hi:[1,1,0]
	v_mov_b32_e32 v64, v67
	v_pk_fma_f32 v[62:63], v[146:147], v[66:67], v[62:63] op_sel_hi:[1,0,1]
	s_nop 0
	v_pk_fma_f32 v[62:63], v[28:29], v[64:65], v[62:63] op_sel_hi:[1,0,1]
	s_waitcnt lgkmcnt(5)
	v_mov_b32_e32 v64, v71
	v_pk_add_f32 v[60:61], v[60:61], v[62:63]
	v_pk_mul_f32 v[62:63], v[152:153], v[68:69]
	s_nop 0
	v_pk_fma_f32 v[62:63], v[154:155], v[68:69], v[62:63] op_sel:[0,0,1] op_sel_hi:[1,1,0]
	s_waitcnt lgkmcnt(0)
	v_mov_b32_e32 v68, v237
	v_pk_fma_f32 v[62:63], v[30:31], v[70:71], v[62:63] op_sel_hi:[1,0,1]
	s_nop 0
	v_pk_fma_f32 v[62:63], v[32:33], v[64:65], v[62:63] op_sel_hi:[1,0,1]
	v_mov_b32_e32 v64, v75
	v_pk_add_f32 v[60:61], v[60:61], v[62:63]
	v_pk_mul_f32 v[62:63], v[156:157], v[72:73]
	s_nop 0
	v_pk_fma_f32 v[62:63], v[158:159], v[72:73], v[62:63] op_sel:[0,0,1] op_sel_hi:[1,1,0]
	s_nop 0
	v_pk_fma_f32 v[62:63], v[34:35], v[74:75], v[62:63] op_sel_hi:[1,0,1]
	s_nop 0
	v_pk_fma_f32 v[62:63], v[36:37], v[64:65], v[62:63] op_sel_hi:[1,0,1]
	v_mov_b32_e32 v64, v79
	v_pk_add_f32 v[60:61], v[60:61], v[62:63]
	v_pk_mul_f32 v[62:63], v[160:161], v[76:77]
	s_nop 0
	v_pk_fma_f32 v[62:63], v[162:163], v[76:77], v[62:63] op_sel:[0,0,1] op_sel_hi:[1,1,0]
	s_nop 0
	v_pk_fma_f32 v[62:63], v[38:39], v[78:79], v[62:63] op_sel_hi:[1,0,1]
	s_nop 0
	v_pk_fma_f32 v[62:63], v[40:41], v[64:65], v[62:63] op_sel_hi:[1,0,1]
	v_mov_b32_e32 v64, v83
	v_pk_add_f32 v[60:61], v[60:61], v[62:63]
	v_pk_mul_f32 v[62:63], v[166:167], v[80:81]
	s_nop 0
	v_pk_fma_f32 v[62:63], v[168:169], v[80:81], v[62:63] op_sel:[0,0,1] op_sel_hi:[1,1,0]
	s_nop 0
	v_pk_fma_f32 v[62:63], v[164:165], v[82:83], v[62:63] op_sel_hi:[1,0,1]
	s_nop 0
	v_pk_fma_f32 v[62:63], v[46:47], v[64:65], v[62:63] op_sel_hi:[1,0,1]
	v_mov_b32_e32 v64, v87
	v_pk_add_f32 v[60:61], v[60:61], v[62:63]
	v_pk_mul_f32 v[62:63], v[170:171], v[84:85]
	s_nop 0
	v_pk_fma_f32 v[62:63], v[172:173], v[84:85], v[62:63] op_sel:[0,0,1] op_sel_hi:[1,1,0]
	s_nop 0
	v_pk_fma_f32 v[62:63], v[48:49], v[86:87], v[62:63] op_sel_hi:[1,0,1]
	s_nop 0
	v_pk_fma_f32 v[62:63], v[50:51], v[64:65], v[62:63] op_sel_hi:[1,0,1]
	s_nop 0
	v_pk_add_f32 v[60:61], v[60:61], v[62:63]
	v_pk_mul_f32 v[62:63], v[176:177], v[234:235]
	s_nop 0
	v_pk_fma_f32 v[62:63], v[178:179], v[234:235], v[62:63] op_sel:[0,0,1] op_sel_hi:[1,1,0]
	s_nop 0
	v_pk_fma_f32 v[66:67], v[174:175], v[236:237], v[62:63] op_sel_hi:[1,0,1]
	ds_read_b128 v[62:65], v1 offset:16384
	v_pk_fma_f32 v[66:67], v[56:57], v[68:69], v[66:67] op_sel_hi:[1,0,1]
	s_nop 0
	v_pk_add_f32 v[60:61], v[60:61], v[66:67]
	ds_read_b128 v[66:69], v1 offset:17408
	s_waitcnt lgkmcnt(1)
	v_pk_mul_f32 v[238:239], v[144:145], v[62:63]
	ds_read_b128 v[70:73], v1 offset:18432
	ds_read_b128 v[74:77], v1 offset:19456
	ds_read_b128 v[78:81], v1 offset:20480
	ds_read_b128 v[82:85], v1 offset:21504
	ds_read_b128 v[86:89], v1 offset:22528
	ds_read_b128 v[234:237], v1 offset:23552
	v_pk_fma_f32 v[62:63], v[6:7], v[62:63], v[238:239] op_sel:[0,0,1] op_sel_hi:[1,1,0]
	s_nop 0
	v_pk_fma_f32 v[62:63], v[142:143], v[64:65], v[62:63] op_sel_hi:[1,0,1]
	v_mov_b32_e32 v64, v65
	v_pk_fma_f32 v[62:63], v[140:141], v[64:65], v[62:63] op_sel_hi:[1,0,1]
	s_waitcnt lgkmcnt(6)
	v_pk_mul_f32 v[64:65], v[148:149], v[66:67]
	v_pk_add_f32 v[62:63], v[62:63], 0 op_sel_hi:[1,0]
	v_pk_fma_f32 v[64:65], v[150:151], v[66:67], v[64:65] op_sel:[0,0,1] op_sel_hi:[1,1,0]
	v_mov_b32_e32 v66, v69
	v_pk_fma_f32 v[64:65], v[146:147], v[68:69], v[64:65] op_sel_hi:[1,0,1]
	s_nop 0
	v_pk_fma_f32 v[64:65], v[28:29], v[66:67], v[64:65] op_sel_hi:[1,0,1]
	s_waitcnt lgkmcnt(5)
	v_mov_b32_e32 v66, v73
	v_pk_add_f32 v[62:63], v[62:63], v[64:65]
	v_pk_mul_f32 v[64:65], v[152:153], v[70:71]
	s_nop 0
	v_pk_fma_f32 v[64:65], v[154:155], v[70:71], v[64:65] op_sel:[0,0,1] op_sel_hi:[1,1,0]
	s_waitcnt lgkmcnt(0)
	v_mov_b32_e32 v70, v237
	v_pk_fma_f32 v[64:65], v[30:31], v[72:73], v[64:65] op_sel_hi:[1,0,1]
	s_nop 0
	v_pk_fma_f32 v[64:65], v[32:33], v[66:67], v[64:65] op_sel_hi:[1,0,1]
	v_mov_b32_e32 v66, v77
	v_pk_add_f32 v[62:63], v[62:63], v[64:65]
	v_pk_mul_f32 v[64:65], v[156:157], v[74:75]
	s_nop 0
	v_pk_fma_f32 v[64:65], v[158:159], v[74:75], v[64:65] op_sel:[0,0,1] op_sel_hi:[1,1,0]
	s_nop 0
	v_pk_fma_f32 v[64:65], v[34:35], v[76:77], v[64:65] op_sel_hi:[1,0,1]
	s_nop 0
	v_pk_fma_f32 v[64:65], v[36:37], v[66:67], v[64:65] op_sel_hi:[1,0,1]
	v_mov_b32_e32 v66, v81
	v_pk_add_f32 v[62:63], v[62:63], v[64:65]
	v_pk_mul_f32 v[64:65], v[160:161], v[78:79]
	s_nop 0
	v_pk_fma_f32 v[64:65], v[162:163], v[78:79], v[64:65] op_sel:[0,0,1] op_sel_hi:[1,1,0]
	s_nop 0
	v_pk_fma_f32 v[64:65], v[38:39], v[80:81], v[64:65] op_sel_hi:[1,0,1]
	s_nop 0
	v_pk_fma_f32 v[64:65], v[40:41], v[66:67], v[64:65] op_sel_hi:[1,0,1]
	v_mov_b32_e32 v66, v85
	v_pk_add_f32 v[62:63], v[62:63], v[64:65]
	v_pk_mul_f32 v[64:65], v[166:167], v[82:83]
	s_nop 0
	v_pk_fma_f32 v[64:65], v[168:169], v[82:83], v[64:65] op_sel:[0,0,1] op_sel_hi:[1,1,0]
	s_nop 0
	v_pk_fma_f32 v[64:65], v[164:165], v[84:85], v[64:65] op_sel_hi:[1,0,1]
	s_nop 0
	v_pk_fma_f32 v[64:65], v[46:47], v[66:67], v[64:65] op_sel_hi:[1,0,1]
	v_mov_b32_e32 v66, v89
	v_pk_add_f32 v[62:63], v[62:63], v[64:65]
	v_pk_mul_f32 v[64:65], v[170:171], v[86:87]
	s_nop 0
	v_pk_fma_f32 v[64:65], v[172:173], v[86:87], v[64:65] op_sel:[0,0,1] op_sel_hi:[1,1,0]
	s_nop 0
	v_pk_fma_f32 v[64:65], v[48:49], v[88:89], v[64:65] op_sel_hi:[1,0,1]
	s_nop 0
	v_pk_fma_f32 v[64:65], v[50:51], v[66:67], v[64:65] op_sel_hi:[1,0,1]
	s_nop 0
	v_pk_add_f32 v[62:63], v[62:63], v[64:65]
	v_pk_mul_f32 v[64:65], v[176:177], v[234:235]
	s_nop 0
	v_pk_fma_f32 v[64:65], v[178:179], v[234:235], v[64:65] op_sel:[0,0,1] op_sel_hi:[1,1,0]
	s_nop 0
	v_pk_fma_f32 v[68:69], v[174:175], v[236:237], v[64:65] op_sel_hi:[1,0,1]
	ds_read_b128 v[64:67], v1 offset:24576
	v_pk_fma_f32 v[68:69], v[56:57], v[70:71], v[68:69] op_sel_hi:[1,0,1]
	s_nop 0
	v_pk_add_f32 v[62:63], v[62:63], v[68:69]
	ds_read_b128 v[68:71], v1 offset:25600
	s_waitcnt lgkmcnt(1)
	v_pk_mul_f32 v[88:89], v[144:145], v[64:65]
	ds_read_b128 v[72:75], v1 offset:26624
	ds_read_b128 v[76:79], v1 offset:27648
	ds_read_b128 v[80:83], v1 offset:28672
	ds_read_b128 v[84:87], v1 offset:29696
	ds_read_b128 v[234:237], v1 offset:30720
	ds_read_b128 v[238:241], v1 offset:31744
	v_pk_fma_f32 v[64:65], v[6:7], v[64:65], v[88:89] op_sel:[0,0,1] op_sel_hi:[1,1,0]
	s_nop 0
	v_pk_fma_f32 v[64:65], v[142:143], v[66:67], v[64:65] op_sel_hi:[1,0,1]
	v_mov_b32_e32 v66, v67
	v_pk_fma_f32 v[64:65], v[140:141], v[66:67], v[64:65] op_sel_hi:[1,0,1]
	s_waitcnt lgkmcnt(6)
	v_pk_mul_f32 v[66:67], v[148:149], v[68:69]
	v_pk_add_f32 v[64:65], v[64:65], 0 op_sel_hi:[1,0]
	v_pk_fma_f32 v[66:67], v[150:151], v[68:69], v[66:67] op_sel:[0,0,1] op_sel_hi:[1,1,0]
	v_mov_b32_e32 v68, v71
	v_pk_fma_f32 v[66:67], v[146:147], v[70:71], v[66:67] op_sel_hi:[1,0,1]
	s_nop 0
	v_pk_fma_f32 v[66:67], v[28:29], v[68:69], v[66:67] op_sel_hi:[1,0,1]
	s_waitcnt lgkmcnt(5)
	v_mov_b32_e32 v68, v75
	v_pk_add_f32 v[64:65], v[64:65], v[66:67]
	v_pk_mul_f32 v[66:67], v[152:153], v[72:73]
	s_nop 0
	v_pk_fma_f32 v[66:67], v[154:155], v[72:73], v[66:67] op_sel:[0,0,1] op_sel_hi:[1,1,0]
	s_waitcnt lgkmcnt(0)
	v_mov_b32_e32 v72, v241
	v_pk_fma_f32 v[66:67], v[30:31], v[74:75], v[66:67] op_sel_hi:[1,0,1]
	s_nop 0
	v_pk_fma_f32 v[66:67], v[32:33], v[68:69], v[66:67] op_sel_hi:[1,0,1]
	v_mov_b32_e32 v68, v79
	v_pk_add_f32 v[64:65], v[64:65], v[66:67]
	v_pk_mul_f32 v[66:67], v[156:157], v[76:77]
	s_nop 0
	v_pk_fma_f32 v[66:67], v[158:159], v[76:77], v[66:67] op_sel:[0,0,1] op_sel_hi:[1,1,0]
	s_nop 0
	v_pk_fma_f32 v[66:67], v[34:35], v[78:79], v[66:67] op_sel_hi:[1,0,1]
	s_nop 0
	v_pk_fma_f32 v[66:67], v[36:37], v[68:69], v[66:67] op_sel_hi:[1,0,1]
	v_mov_b32_e32 v68, v83
	v_pk_add_f32 v[64:65], v[64:65], v[66:67]
	v_pk_mul_f32 v[66:67], v[160:161], v[80:81]
	s_nop 0
	v_pk_fma_f32 v[66:67], v[162:163], v[80:81], v[66:67] op_sel:[0,0,1] op_sel_hi:[1,1,0]
	s_nop 0
	v_pk_fma_f32 v[66:67], v[38:39], v[82:83], v[66:67] op_sel_hi:[1,0,1]
	s_nop 0
	v_pk_fma_f32 v[66:67], v[40:41], v[68:69], v[66:67] op_sel_hi:[1,0,1]
	v_mov_b32_e32 v68, v87
	v_pk_add_f32 v[64:65], v[64:65], v[66:67]
	v_pk_mul_f32 v[66:67], v[166:167], v[84:85]
	s_nop 0
	v_pk_fma_f32 v[66:67], v[168:169], v[84:85], v[66:67] op_sel:[0,0,1] op_sel_hi:[1,1,0]
	s_nop 0
	v_pk_fma_f32 v[66:67], v[164:165], v[86:87], v[66:67] op_sel_hi:[1,0,1]
	s_nop 0
	v_pk_fma_f32 v[66:67], v[46:47], v[68:69], v[66:67] op_sel_hi:[1,0,1]
	v_mov_b32_e32 v68, v237
	v_pk_add_f32 v[64:65], v[64:65], v[66:67]
	v_pk_mul_f32 v[66:67], v[170:171], v[234:235]
	s_nop 0
	v_pk_fma_f32 v[66:67], v[172:173], v[234:235], v[66:67] op_sel:[0,0,1] op_sel_hi:[1,1,0]
	s_nop 0
	v_pk_fma_f32 v[66:67], v[48:49], v[236:237], v[66:67] op_sel_hi:[1,0,1]
	s_nop 0
	v_pk_fma_f32 v[66:67], v[50:51], v[68:69], v[66:67] op_sel_hi:[1,0,1]
	s_nop 0
	v_pk_add_f32 v[64:65], v[64:65], v[66:67]
	v_pk_mul_f32 v[66:67], v[176:177], v[238:239]
	s_nop 0
	v_pk_fma_f32 v[66:67], v[178:179], v[238:239], v[66:67] op_sel:[0,0,1] op_sel_hi:[1,1,0]
	s_nop 0
	v_pk_fma_f32 v[70:71], v[174:175], v[240:241], v[66:67] op_sel_hi:[1,0,1]
	ds_read_b128 v[66:69], v1 offset:32768
	v_pk_fma_f32 v[70:71], v[56:57], v[72:73], v[70:71] op_sel_hi:[1,0,1]
	s_nop 0
	v_pk_add_f32 v[64:65], v[64:65], v[70:71]
	ds_read_b128 v[70:73], v1 offset:33792
	s_waitcnt lgkmcnt(1)
	v_pk_mul_f32 v[242:243], v[144:145], v[66:67]
	ds_read_b128 v[74:77], v1 offset:34816
	ds_read_b128 v[78:81], v1 offset:35840
	ds_read_b128 v[82:85], v1 offset:36864
	ds_read_b128 v[86:89], v1 offset:37888
	ds_read_b128 v[234:237], v1 offset:38912
	ds_read_b128 v[238:241], v1 offset:39936
	v_pk_fma_f32 v[66:67], v[6:7], v[66:67], v[242:243] op_sel:[0,0,1] op_sel_hi:[1,1,0]
	s_nop 0
	v_pk_fma_f32 v[66:67], v[142:143], v[68:69], v[66:67] op_sel_hi:[1,0,1]
	v_mov_b32_e32 v68, v69
	v_pk_fma_f32 v[66:67], v[140:141], v[68:69], v[66:67] op_sel_hi:[1,0,1]
	s_waitcnt lgkmcnt(6)
	v_pk_mul_f32 v[68:69], v[148:149], v[70:71]
	v_pk_add_f32 v[66:67], v[66:67], 0 op_sel_hi:[1,0]
	v_pk_fma_f32 v[68:69], v[150:151], v[70:71], v[68:69] op_sel:[0,0,1] op_sel_hi:[1,1,0]
	v_mov_b32_e32 v70, v73
	v_pk_fma_f32 v[68:69], v[146:147], v[72:73], v[68:69] op_sel_hi:[1,0,1]
	s_nop 0
	v_pk_fma_f32 v[68:69], v[28:29], v[70:71], v[68:69] op_sel_hi:[1,0,1]
	s_waitcnt lgkmcnt(5)
	v_mov_b32_e32 v70, v77
	v_pk_add_f32 v[66:67], v[66:67], v[68:69]
	v_pk_mul_f32 v[68:69], v[152:153], v[74:75]
	s_nop 0
	v_pk_fma_f32 v[68:69], v[154:155], v[74:75], v[68:69] op_sel:[0,0,1] op_sel_hi:[1,1,0]
	s_waitcnt lgkmcnt(0)
	v_mov_b32_e32 v74, v241
	v_pk_fma_f32 v[68:69], v[30:31], v[76:77], v[68:69] op_sel_hi:[1,0,1]
	s_nop 0
	v_pk_fma_f32 v[68:69], v[32:33], v[70:71], v[68:69] op_sel_hi:[1,0,1]
	v_mov_b32_e32 v70, v81
	v_pk_add_f32 v[66:67], v[66:67], v[68:69]
	v_pk_mul_f32 v[68:69], v[156:157], v[78:79]
	s_nop 0
	v_pk_fma_f32 v[68:69], v[158:159], v[78:79], v[68:69] op_sel:[0,0,1] op_sel_hi:[1,1,0]
	s_nop 0
	v_pk_fma_f32 v[68:69], v[34:35], v[80:81], v[68:69] op_sel_hi:[1,0,1]
	s_nop 0
	v_pk_fma_f32 v[68:69], v[36:37], v[70:71], v[68:69] op_sel_hi:[1,0,1]
	v_mov_b32_e32 v70, v85
	v_pk_add_f32 v[66:67], v[66:67], v[68:69]
	v_pk_mul_f32 v[68:69], v[160:161], v[82:83]
	s_nop 0
	v_pk_fma_f32 v[68:69], v[162:163], v[82:83], v[68:69] op_sel:[0,0,1] op_sel_hi:[1,1,0]
	s_nop 0
	v_pk_fma_f32 v[68:69], v[38:39], v[84:85], v[68:69] op_sel_hi:[1,0,1]
	s_nop 0
	v_pk_fma_f32 v[68:69], v[40:41], v[70:71], v[68:69] op_sel_hi:[1,0,1]
	v_mov_b32_e32 v70, v89
	v_pk_add_f32 v[66:67], v[66:67], v[68:69]
	v_pk_mul_f32 v[68:69], v[166:167], v[86:87]
	s_nop 0
	v_pk_fma_f32 v[68:69], v[168:169], v[86:87], v[68:69] op_sel:[0,0,1] op_sel_hi:[1,1,0]
	s_nop 0
	v_pk_fma_f32 v[68:69], v[164:165], v[88:89], v[68:69] op_sel_hi:[1,0,1]
	s_nop 0
	v_pk_fma_f32 v[68:69], v[46:47], v[70:71], v[68:69] op_sel_hi:[1,0,1]
	v_mov_b32_e32 v70, v237
	v_pk_add_f32 v[66:67], v[66:67], v[68:69]
	v_pk_mul_f32 v[68:69], v[170:171], v[234:235]
	s_nop 0
	v_pk_fma_f32 v[68:69], v[172:173], v[234:235], v[68:69] op_sel:[0,0,1] op_sel_hi:[1,1,0]
	s_nop 0
	v_pk_fma_f32 v[68:69], v[48:49], v[236:237], v[68:69] op_sel_hi:[1,0,1]
	s_nop 0
	v_pk_fma_f32 v[68:69], v[50:51], v[70:71], v[68:69] op_sel_hi:[1,0,1]
	s_nop 0
	v_pk_add_f32 v[66:67], v[66:67], v[68:69]
	v_pk_mul_f32 v[68:69], v[176:177], v[238:239]
	s_nop 0
	v_pk_fma_f32 v[68:69], v[178:179], v[238:239], v[68:69] op_sel:[0,0,1] op_sel_hi:[1,1,0]
	s_nop 0
	v_pk_fma_f32 v[72:73], v[174:175], v[240:241], v[68:69] op_sel_hi:[1,0,1]
	ds_read_b128 v[68:71], v1 offset:40960
	v_pk_fma_f32 v[72:73], v[56:57], v[74:75], v[72:73] op_sel_hi:[1,0,1]
	s_nop 0
	v_pk_add_f32 v[66:67], v[66:67], v[72:73]
	ds_read_b128 v[72:75], v1 offset:41984
	s_waitcnt lgkmcnt(1)
	v_pk_mul_f32 v[88:89], v[144:145], v[68:69]
	ds_read_b128 v[76:79], v1 offset:43008
	ds_read_b128 v[80:83], v1 offset:44032
	ds_read_b128 v[84:87], v1 offset:45056
	ds_read_b128 v[234:237], v1 offset:46080
	ds_read_b128 v[238:241], v1 offset:47104
	ds_read_b128 v[242:245], v1 offset:48128
	v_pk_fma_f32 v[68:69], v[6:7], v[68:69], v[88:89] op_sel:[0,0,1] op_sel_hi:[1,1,0]
	s_nop 0
	v_pk_fma_f32 v[68:69], v[142:143], v[70:71], v[68:69] op_sel_hi:[1,0,1]
	v_mov_b32_e32 v70, v71
	v_pk_fma_f32 v[68:69], v[140:141], v[70:71], v[68:69] op_sel_hi:[1,0,1]
	s_waitcnt lgkmcnt(6)
	v_pk_mul_f32 v[70:71], v[148:149], v[72:73]
	v_pk_add_f32 v[68:69], v[68:69], 0 op_sel_hi:[1,0]
	v_pk_fma_f32 v[70:71], v[150:151], v[72:73], v[70:71] op_sel:[0,0,1] op_sel_hi:[1,1,0]
	v_mov_b32_e32 v72, v75
	v_pk_fma_f32 v[70:71], v[146:147], v[74:75], v[70:71] op_sel_hi:[1,0,1]
	s_nop 0
	v_pk_fma_f32 v[70:71], v[28:29], v[72:73], v[70:71] op_sel_hi:[1,0,1]
	s_waitcnt lgkmcnt(5)
	v_mov_b32_e32 v72, v79
	v_pk_add_f32 v[68:69], v[68:69], v[70:71]
	v_pk_mul_f32 v[70:71], v[152:153], v[76:77]
	s_nop 0
	v_pk_fma_f32 v[70:71], v[154:155], v[76:77], v[70:71] op_sel:[0,0,1] op_sel_hi:[1,1,0]
	s_waitcnt lgkmcnt(0)
	v_mov_b32_e32 v76, v245
	v_pk_fma_f32 v[70:71], v[30:31], v[78:79], v[70:71] op_sel_hi:[1,0,1]
	s_nop 0
	v_pk_fma_f32 v[70:71], v[32:33], v[72:73], v[70:71] op_sel_hi:[1,0,1]
	v_mov_b32_e32 v72, v83
	v_pk_add_f32 v[68:69], v[68:69], v[70:71]
	v_pk_mul_f32 v[70:71], v[156:157], v[80:81]
	s_nop 0
	v_pk_fma_f32 v[70:71], v[158:159], v[80:81], v[70:71] op_sel:[0,0,1] op_sel_hi:[1,1,0]
	s_nop 0
	v_pk_fma_f32 v[70:71], v[34:35], v[82:83], v[70:71] op_sel_hi:[1,0,1]
	s_nop 0
	v_pk_fma_f32 v[70:71], v[36:37], v[72:73], v[70:71] op_sel_hi:[1,0,1]
	v_mov_b32_e32 v72, v87
	v_pk_add_f32 v[68:69], v[68:69], v[70:71]
	v_pk_mul_f32 v[70:71], v[160:161], v[84:85]
	s_nop 0
	v_pk_fma_f32 v[70:71], v[162:163], v[84:85], v[70:71] op_sel:[0,0,1] op_sel_hi:[1,1,0]
	s_nop 0
	v_pk_fma_f32 v[70:71], v[38:39], v[86:87], v[70:71] op_sel_hi:[1,0,1]
	s_nop 0
	v_pk_fma_f32 v[70:71], v[40:41], v[72:73], v[70:71] op_sel_hi:[1,0,1]
	v_mov_b32_e32 v72, v237
	v_pk_add_f32 v[68:69], v[68:69], v[70:71]
	v_pk_mul_f32 v[70:71], v[166:167], v[234:235]
	s_nop 0
	v_pk_fma_f32 v[70:71], v[168:169], v[234:235], v[70:71] op_sel:[0,0,1] op_sel_hi:[1,1,0]
	s_nop 0
	v_pk_fma_f32 v[70:71], v[164:165], v[236:237], v[70:71] op_sel_hi:[1,0,1]
	s_nop 0
	v_pk_fma_f32 v[70:71], v[46:47], v[72:73], v[70:71] op_sel_hi:[1,0,1]
	v_mov_b32_e32 v72, v241
	v_pk_add_f32 v[68:69], v[68:69], v[70:71]
	v_pk_mul_f32 v[70:71], v[170:171], v[238:239]
	s_nop 0
	v_pk_fma_f32 v[70:71], v[172:173], v[238:239], v[70:71] op_sel:[0,0,1] op_sel_hi:[1,1,0]
	s_nop 0
	v_pk_fma_f32 v[70:71], v[48:49], v[240:241], v[70:71] op_sel_hi:[1,0,1]
	s_nop 0
	v_pk_fma_f32 v[70:71], v[50:51], v[72:73], v[70:71] op_sel_hi:[1,0,1]
	s_nop 0
	v_pk_add_f32 v[68:69], v[68:69], v[70:71]
	v_pk_mul_f32 v[70:71], v[176:177], v[242:243]
	s_nop 0
	v_pk_fma_f32 v[70:71], v[178:179], v[242:243], v[70:71] op_sel:[0,0,1] op_sel_hi:[1,1,0]
	s_nop 0
	v_pk_fma_f32 v[74:75], v[174:175], v[244:245], v[70:71] op_sel_hi:[1,0,1]
	ds_read_b128 v[70:73], v1 offset:49152
	v_pk_fma_f32 v[74:75], v[56:57], v[76:77], v[74:75] op_sel_hi:[1,0,1]
	s_nop 0
	v_pk_add_f32 v[68:69], v[68:69], v[74:75]
	ds_read_b128 v[74:77], v1 offset:50176
	s_waitcnt lgkmcnt(1)
	v_pk_mul_f32 v[246:247], v[144:145], v[70:71]
	ds_read_b128 v[78:81], v1 offset:51200
	ds_read_b128 v[82:85], v1 offset:52224
	ds_read_b128 v[86:89], v1 offset:53248
	ds_read_b128 v[234:237], v1 offset:54272
	ds_read_b128 v[238:241], v1 offset:55296
	ds_read_b128 v[242:245], v1 offset:56320
	v_pk_fma_f32 v[70:71], v[6:7], v[70:71], v[246:247] op_sel:[0,0,1] op_sel_hi:[1,1,0]
	s_nop 0
	v_pk_fma_f32 v[70:71], v[142:143], v[72:73], v[70:71] op_sel_hi:[1,0,1]
	v_mov_b32_e32 v72, v73
	v_pk_fma_f32 v[70:71], v[140:141], v[72:73], v[70:71] op_sel_hi:[1,0,1]
	s_waitcnt lgkmcnt(6)
	v_pk_mul_f32 v[72:73], v[148:149], v[74:75]
	v_pk_add_f32 v[70:71], v[70:71], 0 op_sel_hi:[1,0]
	v_pk_fma_f32 v[72:73], v[150:151], v[74:75], v[72:73] op_sel:[0,0,1] op_sel_hi:[1,1,0]
	v_mov_b32_e32 v74, v77
	v_pk_fma_f32 v[72:73], v[146:147], v[76:77], v[72:73] op_sel_hi:[1,0,1]
	s_nop 0
	v_pk_fma_f32 v[72:73], v[28:29], v[74:75], v[72:73] op_sel_hi:[1,0,1]
	s_waitcnt lgkmcnt(5)
	v_mov_b32_e32 v74, v81
	v_pk_add_f32 v[70:71], v[70:71], v[72:73]
	v_pk_mul_f32 v[72:73], v[152:153], v[78:79]
	s_nop 0
	v_pk_fma_f32 v[72:73], v[154:155], v[78:79], v[72:73] op_sel:[0,0,1] op_sel_hi:[1,1,0]
	s_waitcnt lgkmcnt(0)
	v_mov_b32_e32 v78, v245
	v_pk_fma_f32 v[72:73], v[30:31], v[80:81], v[72:73] op_sel_hi:[1,0,1]
	s_nop 0
	v_pk_fma_f32 v[72:73], v[32:33], v[74:75], v[72:73] op_sel_hi:[1,0,1]
	v_mov_b32_e32 v74, v85
	v_pk_add_f32 v[70:71], v[70:71], v[72:73]
	v_pk_mul_f32 v[72:73], v[156:157], v[82:83]
	s_nop 0
	v_pk_fma_f32 v[72:73], v[158:159], v[82:83], v[72:73] op_sel:[0,0,1] op_sel_hi:[1,1,0]
	s_nop 0
	v_pk_fma_f32 v[72:73], v[34:35], v[84:85], v[72:73] op_sel_hi:[1,0,1]
	s_nop 0
	v_pk_fma_f32 v[72:73], v[36:37], v[74:75], v[72:73] op_sel_hi:[1,0,1]
	v_mov_b32_e32 v74, v89
	v_pk_add_f32 v[70:71], v[70:71], v[72:73]
	v_pk_mul_f32 v[72:73], v[160:161], v[86:87]
	s_nop 0
	v_pk_fma_f32 v[72:73], v[162:163], v[86:87], v[72:73] op_sel:[0,0,1] op_sel_hi:[1,1,0]
	s_nop 0
	v_pk_fma_f32 v[72:73], v[38:39], v[88:89], v[72:73] op_sel_hi:[1,0,1]
	s_nop 0
	v_pk_fma_f32 v[72:73], v[40:41], v[74:75], v[72:73] op_sel_hi:[1,0,1]
	v_mov_b32_e32 v74, v237
	v_pk_add_f32 v[70:71], v[70:71], v[72:73]
	v_pk_mul_f32 v[72:73], v[166:167], v[234:235]
	s_nop 0
	v_pk_fma_f32 v[72:73], v[168:169], v[234:235], v[72:73] op_sel:[0,0,1] op_sel_hi:[1,1,0]
	s_nop 0
	v_pk_fma_f32 v[72:73], v[164:165], v[236:237], v[72:73] op_sel_hi:[1,0,1]
	s_nop 0
	v_pk_fma_f32 v[72:73], v[46:47], v[74:75], v[72:73] op_sel_hi:[1,0,1]
	v_mov_b32_e32 v74, v241
	v_pk_add_f32 v[70:71], v[70:71], v[72:73]
	v_pk_mul_f32 v[72:73], v[170:171], v[238:239]
	s_nop 0
	v_pk_fma_f32 v[72:73], v[172:173], v[238:239], v[72:73] op_sel:[0,0,1] op_sel_hi:[1,1,0]
	s_nop 0
	v_pk_fma_f32 v[72:73], v[48:49], v[240:241], v[72:73] op_sel_hi:[1,0,1]
	s_nop 0
	v_pk_fma_f32 v[72:73], v[50:51], v[74:75], v[72:73] op_sel_hi:[1,0,1]
	s_nop 0
	v_pk_add_f32 v[70:71], v[70:71], v[72:73]
	v_pk_mul_f32 v[72:73], v[176:177], v[242:243]
	s_nop 0
	v_pk_fma_f32 v[72:73], v[178:179], v[242:243], v[72:73] op_sel:[0,0,1] op_sel_hi:[1,1,0]
	s_nop 0
	v_pk_fma_f32 v[76:77], v[174:175], v[244:245], v[72:73] op_sel_hi:[1,0,1]
	ds_read_b128 v[72:75], v1 offset:57344
	v_pk_fma_f32 v[76:77], v[56:57], v[78:79], v[76:77] op_sel_hi:[1,0,1]
	s_nop 0
	v_pk_add_f32 v[70:71], v[70:71], v[76:77]
	ds_read_b128 v[76:79], v1 offset:58368
	s_waitcnt lgkmcnt(1)
	v_pk_mul_f32 v[88:89], v[144:145], v[72:73]
	ds_read_b128 v[80:83], v1 offset:59392
	ds_read_b128 v[84:87], v1 offset:60416
	ds_read_b128 v[234:237], v1 offset:61440
	ds_read_b128 v[238:241], v1 offset:62464
	ds_read_b128 v[242:245], v1 offset:63488
	ds_read_b128 v[246:249], v1 offset:64512
	v_pk_fma_f32 v[72:73], v[6:7], v[72:73], v[88:89] op_sel:[0,0,1] op_sel_hi:[1,1,0]
	s_nop 0
	v_pk_fma_f32 v[72:73], v[142:143], v[74:75], v[72:73] op_sel_hi:[1,0,1]
	v_mov_b32_e32 v74, v75
	v_pk_fma_f32 v[72:73], v[140:141], v[74:75], v[72:73] op_sel_hi:[1,0,1]
	s_waitcnt lgkmcnt(6)
	v_pk_mul_f32 v[74:75], v[148:149], v[76:77]
	v_pk_add_f32 v[72:73], v[72:73], 0 op_sel_hi:[1,0]
	v_pk_fma_f32 v[74:75], v[150:151], v[76:77], v[74:75] op_sel:[0,0,1] op_sel_hi:[1,1,0]
	v_mov_b32_e32 v76, v79
	v_pk_fma_f32 v[74:75], v[146:147], v[78:79], v[74:75] op_sel_hi:[1,0,1]
	s_nop 0
	v_pk_fma_f32 v[74:75], v[28:29], v[76:77], v[74:75] op_sel_hi:[1,0,1]
	s_waitcnt lgkmcnt(5)
	v_mov_b32_e32 v76, v83
	v_pk_add_f32 v[72:73], v[72:73], v[74:75]
	v_pk_mul_f32 v[74:75], v[152:153], v[80:81]
	s_nop 0
	v_pk_fma_f32 v[74:75], v[154:155], v[80:81], v[74:75] op_sel:[0,0,1] op_sel_hi:[1,1,0]
	s_waitcnt lgkmcnt(0)
	v_mov_b32_e32 v80, v249
	v_pk_fma_f32 v[74:75], v[30:31], v[82:83], v[74:75] op_sel_hi:[1,0,1]
	v_add_u32_e32 v82, 0x10800, v1
	v_pk_fma_f32 v[74:75], v[32:33], v[76:77], v[74:75] op_sel_hi:[1,0,1]
	v_mov_b32_e32 v76, v87
	v_pk_add_f32 v[72:73], v[72:73], v[74:75]
	v_pk_mul_f32 v[74:75], v[156:157], v[84:85]
	s_nop 0
	v_pk_fma_f32 v[74:75], v[158:159], v[84:85], v[74:75] op_sel:[0,0,1] op_sel_hi:[1,1,0]
	ds_read_b128 v[82:85], v82
	v_pk_fma_f32 v[74:75], v[34:35], v[86:87], v[74:75] op_sel_hi:[1,0,1]
	v_add_u32_e32 v86, 0x10c00, v1
	v_pk_fma_f32 v[74:75], v[36:37], v[76:77], v[74:75] op_sel_hi:[1,0,1]
	v_mov_b32_e32 v76, v237
	v_pk_add_f32 v[72:73], v[72:73], v[74:75]
	v_pk_mul_f32 v[74:75], v[160:161], v[234:235]
	ds_read_b128 v[86:89], v86
	v_pk_fma_f32 v[74:75], v[162:163], v[234:235], v[74:75] op_sel:[0,0,1] op_sel_hi:[1,1,0]
	s_nop 0
	v_pk_fma_f32 v[74:75], v[38:39], v[236:237], v[74:75] op_sel_hi:[1,0,1]
	ds_read_b128 v[234:237], v92
	v_pk_fma_f32 v[74:75], v[40:41], v[76:77], v[74:75] op_sel_hi:[1,0,1]
	v_mov_b32_e32 v76, v241
	v_pk_add_f32 v[72:73], v[72:73], v[74:75]
	v_pk_mul_f32 v[74:75], v[166:167], v[238:239]
	s_nop 0
	v_pk_fma_f32 v[74:75], v[168:169], v[238:239], v[74:75] op_sel:[0,0,1] op_sel_hi:[1,1,0]
	s_nop 0
	v_pk_fma_f32 v[74:75], v[164:165], v[240:241], v[74:75] op_sel_hi:[1,0,1]
	s_nop 0
	v_pk_fma_f32 v[74:75], v[46:47], v[76:77], v[74:75] op_sel_hi:[1,0,1]
	v_mov_b32_e32 v76, v245
	v_pk_add_f32 v[72:73], v[72:73], v[74:75]
	v_pk_mul_f32 v[74:75], v[170:171], v[242:243]
	s_nop 0
	v_pk_fma_f32 v[74:75], v[172:173], v[242:243], v[74:75] op_sel:[0,0,1] op_sel_hi:[1,1,0]
	s_nop 0
	v_pk_fma_f32 v[74:75], v[48:49], v[244:245], v[74:75] op_sel_hi:[1,0,1]
	s_nop 0
	v_pk_fma_f32 v[74:75], v[50:51], v[76:77], v[74:75] op_sel_hi:[1,0,1]
	s_nop 0
	v_pk_add_f32 v[72:73], v[72:73], v[74:75]
	v_pk_mul_f32 v[74:75], v[176:177], v[246:247]
	s_nop 0
	v_pk_fma_f32 v[74:75], v[178:179], v[246:247], v[74:75] op_sel:[0,0,1] op_sel_hi:[1,1,0]
	s_nop 0
	v_pk_fma_f32 v[78:79], v[174:175], v[248:249], v[74:75] op_sel_hi:[1,0,1]
	v_add_u32_e32 v74, 0x10000, v1
	ds_read_b128 v[74:77], v74
	v_pk_fma_f32 v[78:79], v[56:57], v[80:81], v[78:79] op_sel_hi:[1,0,1]
	s_nop 0
	v_pk_add_f32 v[72:73], v[72:73], v[78:79]
	v_add_u32_e32 v78, 0x10400, v1
	ds_read_b128 v[78:81], v78
	s_waitcnt lgkmcnt(1)
	v_pk_mul_f32 v[250:251], v[144:145], v[74:75]
	s_nop 0
	v_pk_fma_f32 v[74:75], v[6:7], v[74:75], v[250:251] op_sel:[0,0,1] op_sel_hi:[1,1,0]
	s_nop 0
	v_pk_fma_f32 v[74:75], v[142:143], v[76:77], v[74:75] op_sel_hi:[1,0,1]
	v_mov_b32_e32 v76, v77
	v_pk_fma_f32 v[74:75], v[140:141], v[76:77], v[74:75] op_sel_hi:[1,0,1]
	s_waitcnt lgkmcnt(0)
	v_pk_mul_f32 v[76:77], v[148:149], v[78:79]
	v_pk_add_f32 v[74:75], v[74:75], 0 op_sel_hi:[1,0]
	v_pk_fma_f32 v[76:77], v[150:151], v[78:79], v[76:77] op_sel:[0,0,1] op_sel_hi:[1,1,0]
	v_mov_b32_e32 v78, v81
	v_pk_fma_f32 v[76:77], v[146:147], v[80:81], v[76:77] op_sel_hi:[1,0,1]
	s_nop 0
	v_pk_fma_f32 v[76:77], v[28:29], v[78:79], v[76:77] op_sel_hi:[1,0,1]
	v_mov_b32_e32 v78, v85
	v_pk_add_f32 v[74:75], v[74:75], v[76:77]
	v_pk_mul_f32 v[76:77], v[152:153], v[82:83]
	s_nop 0
	v_pk_fma_f32 v[76:77], v[154:155], v[82:83], v[76:77] op_sel:[0,0,1] op_sel_hi:[1,1,0]
	s_nop 0
	v_pk_fma_f32 v[76:77], v[30:31], v[84:85], v[76:77] op_sel_hi:[1,0,1]
	v_add_u32_e32 v84, 0x12800, v1
	v_pk_fma_f32 v[76:77], v[32:33], v[78:79], v[76:77] op_sel_hi:[1,0,1]
	v_mov_b32_e32 v78, v89
	v_pk_add_f32 v[74:75], v[74:75], v[76:77]
	v_pk_mul_f32 v[76:77], v[156:157], v[86:87]
	s_nop 0
	v_pk_fma_f32 v[76:77], v[158:159], v[86:87], v[76:77] op_sel:[0,0,1] op_sel_hi:[1,1,0]
	ds_read_b128 v[84:87], v84
	v_add_u32_e32 v92, 0x11400, v1
	v_pk_fma_f32 v[76:77], v[34:35], v[88:89], v[76:77] op_sel_hi:[1,0,1]
	ds_read_b128 v[238:241], v92
	v_pk_fma_f32 v[76:77], v[36:37], v[78:79], v[76:77] op_sel_hi:[1,0,1]
	v_add_u32_e32 v92, 0x11800, v1
	v_pk_add_f32 v[74:75], v[74:75], v[76:77]
	v_pk_mul_f32 v[76:77], v[160:161], v[234:235]
	v_mov_b32_e32 v78, v237
	v_pk_fma_f32 v[76:77], v[162:163], v[234:235], v[76:77] op_sel:[0,0,1] op_sel_hi:[1,1,0]
	ds_read_b128 v[242:245], v92
	v_pk_fma_f32 v[76:77], v[38:39], v[236:237], v[76:77] op_sel_hi:[1,0,1]
	v_add_u32_e32 v92, 0x11c00, v1
	v_pk_fma_f32 v[76:77], v[40:41], v[78:79], v[76:77] op_sel_hi:[1,0,1]
	s_waitcnt lgkmcnt(1)
	v_mov_b32_e32 v78, v241
	v_pk_add_f32 v[74:75], v[74:75], v[76:77]
	v_pk_mul_f32 v[76:77], v[166:167], v[238:239]
	ds_read_b128 v[246:249], v92
	v_pk_fma_f32 v[76:77], v[168:169], v[238:239], v[76:77] op_sel:[0,0,1] op_sel_hi:[1,1,0]
	v_add_u32_e32 v92, 0x12c00, v1
	v_pk_fma_f32 v[76:77], v[164:165], v[240:241], v[76:77] op_sel_hi:[1,0,1]
	ds_read_b128 v[234:237], v92
	v_pk_fma_f32 v[76:77], v[46:47], v[78:79], v[76:77] op_sel_hi:[1,0,1]
	s_waitcnt lgkmcnt(2)
	v_mov_b32_e32 v78, v245
	v_pk_add_f32 v[74:75], v[74:75], v[76:77]
	v_pk_mul_f32 v[76:77], v[170:171], v[242:243]
	s_waitcnt lgkmcnt(1)
	v_mov_b32_e32 v82, v249
	v_pk_fma_f32 v[76:77], v[172:173], v[242:243], v[76:77] op_sel:[0,0,1] op_sel_hi:[1,1,0]
	s_nop 0
	v_pk_fma_f32 v[76:77], v[48:49], v[244:245], v[76:77] op_sel_hi:[1,0,1]
	s_nop 0
	v_pk_fma_f32 v[76:77], v[50:51], v[78:79], v[76:77] op_sel_hi:[1,0,1]
	s_nop 0
	v_pk_add_f32 v[74:75], v[74:75], v[76:77]
	v_pk_mul_f32 v[76:77], v[176:177], v[246:247]
	s_nop 0
	v_pk_fma_f32 v[76:77], v[178:179], v[246:247], v[76:77] op_sel:[0,0,1] op_sel_hi:[1,1,0]
	s_nop 0
	v_pk_fma_f32 v[80:81], v[174:175], v[248:249], v[76:77] op_sel_hi:[1,0,1]
	v_add_u32_e32 v76, 0x12000, v1
	ds_read_b128 v[76:79], v76
	v_pk_fma_f32 v[80:81], v[56:57], v[82:83], v[80:81] op_sel_hi:[1,0,1]
	s_nop 0
	v_pk_add_f32 v[74:75], v[74:75], v[80:81]
	v_add_u32_e32 v80, 0x12400, v1
	ds_read_b128 v[80:83], v80
	s_waitcnt lgkmcnt(1)
	v_pk_mul_f32 v[88:89], v[144:145], v[76:77]
	s_nop 0
	v_pk_fma_f32 v[76:77], v[6:7], v[76:77], v[88:89] op_sel:[0,0,1] op_sel_hi:[1,1,0]
	s_nop 0
	v_pk_fma_f32 v[76:77], v[142:143], v[78:79], v[76:77] op_sel_hi:[1,0,1]
	v_mov_b32_e32 v78, v79
	v_pk_fma_f32 v[76:77], v[140:141], v[78:79], v[76:77] op_sel_hi:[1,0,1]
	s_waitcnt lgkmcnt(0)
	v_pk_mul_f32 v[78:79], v[148:149], v[80:81]
	v_pk_add_f32 v[76:77], v[76:77], 0 op_sel_hi:[1,0]
	v_pk_fma_f32 v[78:79], v[150:151], v[80:81], v[78:79] op_sel:[0,0,1] op_sel_hi:[1,1,0]
	v_mov_b32_e32 v80, v83
	v_pk_fma_f32 v[78:79], v[146:147], v[82:83], v[78:79] op_sel_hi:[1,0,1]
	s_nop 0
	v_pk_fma_f32 v[78:79], v[28:29], v[80:81], v[78:79] op_sel_hi:[1,0,1]
	v_mov_b32_e32 v80, v87
	v_pk_add_f32 v[76:77], v[76:77], v[78:79]
	v_pk_mul_f32 v[78:79], v[152:153], v[84:85]
	s_nop 0
	v_pk_fma_f32 v[78:79], v[154:155], v[84:85], v[78:79] op_sel:[0,0,1] op_sel_hi:[1,1,0]
	s_nop 0
	v_pk_fma_f32 v[78:79], v[30:31], v[86:87], v[78:79] op_sel_hi:[1,0,1]
	v_add_u32_e32 v86, 0x14800, v1
	ds_read_b128 v[86:89], v86
	v_add_u32_e32 v92, 0x13000, v1
	ds_read_b128 v[238:241], v92
	v_pk_fma_f32 v[78:79], v[32:33], v[80:81], v[78:79] op_sel_hi:[1,0,1]
	v_add_u32_e32 v92, 0x13400, v1
	v_pk_add_f32 v[76:77], v[76:77], v[78:79]
	v_pk_mul_f32 v[78:79], v[156:157], v[234:235]
	v_mov_b32_e32 v80, v237
	v_pk_fma_f32 v[78:79], v[158:159], v[234:235], v[78:79] op_sel:[0,0,1] op_sel_hi:[1,1,0]
	ds_read_b128 v[242:245], v92
	v_pk_fma_f32 v[78:79], v[34:35], v[236:237], v[78:79] op_sel_hi:[1,0,1]
	v_add_u32_e32 v92, 0x13800, v1
	v_pk_fma_f32 v[78:79], v[36:37], v[80:81], v[78:79] op_sel_hi:[1,0,1]
	s_waitcnt lgkmcnt(1)
	v_mov_b32_e32 v80, v241
	v_pk_add_f32 v[76:77], v[76:77], v[78:79]
	v_pk_mul_f32 v[78:79], v[160:161], v[238:239]
	ds_read_b128 v[246:249], v92
	v_pk_fma_f32 v[78:79], v[162:163], v[238:239], v[78:79] op_sel:[0,0,1] op_sel_hi:[1,1,0]
	v_add_u32_e32 v92, 0x13c00, v1
	v_pk_fma_f32 v[78:79], v[38:39], v[240:241], v[78:79] op_sel_hi:[1,0,1]
	ds_read_b128 v[250:253], v92
	v_pk_fma_f32 v[78:79], v[40:41], v[80:81], v[78:79] op_sel_hi:[1,0,1]
	s_waitcnt lgkmcnt(2)
	v_mov_b32_e32 v80, v245
	v_pk_add_f32 v[76:77], v[76:77], v[78:79]
	v_pk_mul_f32 v[78:79], v[166:167], v[242:243]
	s_waitcnt lgkmcnt(0)
	v_mov_b32_e32 v84, v253
	v_pk_fma_f32 v[78:79], v[168:169], v[242:243], v[78:79] op_sel:[0,0,1] op_sel_hi:[1,1,0]
	v_add_u32_e32 v92, 0x14c00, v1
	v_pk_fma_f32 v[78:79], v[164:165], v[244:245], v[78:79] op_sel_hi:[1,0,1]
	s_nop 0
	v_pk_fma_f32 v[78:79], v[46:47], v[80:81], v[78:79] op_sel_hi:[1,0,1]
	v_mov_b32_e32 v80, v249
	v_pk_add_f32 v[76:77], v[76:77], v[78:79]
	v_pk_mul_f32 v[78:79], v[170:171], v[246:247]
	s_nop 0
	v_pk_fma_f32 v[78:79], v[172:173], v[246:247], v[78:79] op_sel:[0,0,1] op_sel_hi:[1,1,0]
	s_nop 0
	v_pk_fma_f32 v[78:79], v[48:49], v[248:249], v[78:79] op_sel_hi:[1,0,1]
	s_nop 0
	v_pk_fma_f32 v[78:79], v[50:51], v[80:81], v[78:79] op_sel_hi:[1,0,1]
	s_nop 0
	v_pk_add_f32 v[76:77], v[76:77], v[78:79]
	v_pk_mul_f32 v[78:79], v[176:177], v[250:251]
	s_nop 0
	v_pk_fma_f32 v[78:79], v[178:179], v[250:251], v[78:79] op_sel:[0,0,1] op_sel_hi:[1,1,0]
	s_nop 0
	v_pk_fma_f32 v[82:83], v[174:175], v[252:253], v[78:79] op_sel_hi:[1,0,1]
	v_add_u32_e32 v78, 0x14000, v1
	ds_read_b128 v[78:81], v78
	v_pk_fma_f32 v[82:83], v[56:57], v[84:85], v[82:83] op_sel_hi:[1,0,1]
	s_nop 0
	v_pk_add_f32 v[76:77], v[76:77], v[82:83]
	v_add_u32_e32 v82, 0x14400, v1
	ds_read_b128 v[82:85], v82
	s_waitcnt lgkmcnt(1)
	v_pk_mul_f32 v[230:231], v[144:145], v[78:79]
	ds_read_b128 v[234:237], v92
	ds_read_b128 v[238:241], v129
	ds_read_b128 v[242:245], v139
	ds_read_b128 v[246:249], v91
	ds_read_b128 v[250:253], v187
	v_pk_fma_f32 v[78:79], v[6:7], v[78:79], v[230:231] op_sel:[0,0,1] op_sel_hi:[1,1,0]
	s_nop 0
	v_pk_fma_f32 v[78:79], v[142:143], v[80:81], v[78:79] op_sel_hi:[1,0,1]
	v_mov_b32_e32 v80, v81
	v_pk_fma_f32 v[78:79], v[140:141], v[80:81], v[78:79] op_sel_hi:[1,0,1]
	s_waitcnt lgkmcnt(5)
	v_pk_mul_f32 v[80:81], v[148:149], v[82:83]
	v_pk_add_f32 v[78:79], v[78:79], 0 op_sel_hi:[1,0]
	v_pk_fma_f32 v[80:81], v[150:151], v[82:83], v[80:81] op_sel:[0,0,1] op_sel_hi:[1,1,0]
	v_mov_b32_e32 v82, v85
	v_pk_fma_f32 v[80:81], v[146:147], v[84:85], v[80:81] op_sel_hi:[1,0,1]
	s_nop 0
	v_pk_fma_f32 v[80:81], v[28:29], v[82:83], v[80:81] op_sel_hi:[1,0,1]
	v_mov_b32_e32 v82, v89
	v_pk_add_f32 v[78:79], v[78:79], v[80:81]
	v_pk_mul_f32 v[80:81], v[152:153], v[86:87]
	s_nop 0
	v_pk_fma_f32 v[80:81], v[154:155], v[86:87], v[80:81] op_sel:[0,0,1] op_sel_hi:[1,1,0]
	s_waitcnt lgkmcnt(0)
	v_mov_b32_e32 v86, v253
	v_pk_fma_f32 v[80:81], v[30:31], v[88:89], v[80:81] op_sel_hi:[1,0,1]
	s_nop 0
	v_pk_fma_f32 v[80:81], v[32:33], v[82:83], v[80:81] op_sel_hi:[1,0,1]
	v_mov_b32_e32 v82, v237
	v_pk_add_f32 v[78:79], v[78:79], v[80:81]
	v_pk_mul_f32 v[80:81], v[156:157], v[234:235]
	s_nop 0
	v_pk_fma_f32 v[80:81], v[158:159], v[234:235], v[80:81] op_sel:[0,0,1] op_sel_hi:[1,1,0]
	s_nop 0
	v_pk_fma_f32 v[80:81], v[34:35], v[236:237], v[80:81] op_sel_hi:[1,0,1]
	s_nop 0
	v_pk_fma_f32 v[80:81], v[36:37], v[82:83], v[80:81] op_sel_hi:[1,0,1]
	v_mov_b32_e32 v82, v241
	v_pk_add_f32 v[78:79], v[78:79], v[80:81]
	v_pk_mul_f32 v[80:81], v[160:161], v[238:239]
	s_nop 0
	v_pk_fma_f32 v[80:81], v[162:163], v[238:239], v[80:81] op_sel:[0,0,1] op_sel_hi:[1,1,0]
	s_nop 0
	v_pk_fma_f32 v[80:81], v[38:39], v[240:241], v[80:81] op_sel_hi:[1,0,1]
	s_nop 0
	v_pk_fma_f32 v[80:81], v[40:41], v[82:83], v[80:81] op_sel_hi:[1,0,1]
	v_mov_b32_e32 v82, v245
	v_pk_add_f32 v[78:79], v[78:79], v[80:81]
	v_pk_mul_f32 v[80:81], v[166:167], v[242:243]
	s_nop 0
	v_pk_fma_f32 v[80:81], v[168:169], v[242:243], v[80:81] op_sel:[0,0,1] op_sel_hi:[1,1,0]
	s_nop 0
	v_pk_fma_f32 v[80:81], v[164:165], v[244:245], v[80:81] op_sel_hi:[1,0,1]
	s_nop 0
	v_pk_fma_f32 v[80:81], v[46:47], v[82:83], v[80:81] op_sel_hi:[1,0,1]
	v_mov_b32_e32 v82, v249
	v_pk_add_f32 v[78:79], v[78:79], v[80:81]
	v_pk_mul_f32 v[80:81], v[170:171], v[246:247]
	s_nop 0
	v_pk_fma_f32 v[80:81], v[172:173], v[246:247], v[80:81] op_sel:[0,0,1] op_sel_hi:[1,1,0]
	s_nop 0
	v_pk_fma_f32 v[80:81], v[48:49], v[248:249], v[80:81] op_sel_hi:[1,0,1]
	s_nop 0
	v_pk_fma_f32 v[80:81], v[50:51], v[82:83], v[80:81] op_sel_hi:[1,0,1]
	s_nop 0
	v_pk_add_f32 v[78:79], v[78:79], v[80:81]
	v_pk_mul_f32 v[80:81], v[176:177], v[250:251]
	s_nop 0
	v_pk_fma_f32 v[80:81], v[178:179], v[250:251], v[80:81] op_sel:[0,0,1] op_sel_hi:[1,1,0]
	s_nop 0
	v_pk_fma_f32 v[84:85], v[174:175], v[252:253], v[80:81] op_sel_hi:[1,0,1]
	ds_read_b128 v[80:83], v188
	v_pk_fma_f32 v[84:85], v[56:57], v[86:87], v[84:85] op_sel_hi:[1,0,1]
	s_nop 0
	v_pk_add_f32 v[78:79], v[78:79], v[84:85]
	ds_read_b128 v[84:87], v189
	s_waitcnt lgkmcnt(1)
	v_pk_mul_f32 v[88:89], v[144:145], v[80:81]
	ds_read_b128 v[234:237], v190
	ds_read_b128 v[238:241], v191
	ds_read_b128 v[242:245], v192
	ds_read_b128 v[246:249], v193
	v_pk_fma_f32 v[80:81], v[6:7], v[80:81], v[88:89] op_sel:[0,0,1] op_sel_hi:[1,1,0]
	v_mov_b32_e32 v92, v83
	s_waitcnt lgkmcnt(4)
	v_pk_mul_f32 v[230:231], v[148:149], v[84:85]
	v_pk_fma_f32 v[88:89], v[142:143], v[82:83], v[80:81] op_sel_hi:[1,0,1]
	v_pk_fma_f32 v[84:85], v[150:151], v[84:85], v[230:231] op_sel:[0,0,1] op_sel_hi:[1,1,0]
	v_pk_fma_f32 v[88:89], v[140:141], v[92:93], v[88:89] op_sel_hi:[1,0,1]
	v_pk_fma_f32 v[84:85], v[146:147], v[86:87], v[84:85] op_sel_hi:[1,0,1]
	v_mov_b32_e32 v86, v87
	v_pk_fma_f32 v[84:85], v[28:29], v[86:87], v[84:85] op_sel_hi:[1,0,1]
	s_waitcnt lgkmcnt(3)
	v_pk_mul_f32 v[86:87], v[152:153], v[234:235]
	v_pk_add_f32 v[88:89], v[88:89], 0 op_sel_hi:[1,0]
	v_pk_fma_f32 v[86:87], v[154:155], v[234:235], v[86:87] op_sel:[0,0,1] op_sel_hi:[1,1,0]
	v_pk_add_f32 v[84:85], v[88:89], v[84:85]
	v_pk_fma_f32 v[86:87], v[30:31], v[236:237], v[86:87] op_sel_hi:[1,0,1]
	v_mov_b32_e32 v88, v237
	v_pk_fma_f32 v[86:87], v[32:33], v[88:89], v[86:87] op_sel_hi:[1,0,1]
	s_waitcnt lgkmcnt(2)
	v_mov_b32_e32 v88, v241
	v_pk_add_f32 v[84:85], v[84:85], v[86:87]
	v_pk_mul_f32 v[86:87], v[156:157], v[238:239]
	ds_read_b128 v[80:83], v194
	ds_read_b128 v[250:253], v195
	v_pk_fma_f32 v[86:87], v[158:159], v[238:239], v[86:87] op_sel:[0,0,1] op_sel_hi:[1,1,0]
	s_nop 0
	v_pk_fma_f32 v[86:87], v[34:35], v[240:241], v[86:87] op_sel_hi:[1,0,1]
	s_nop 0
	v_pk_fma_f32 v[86:87], v[36:37], v[88:89], v[86:87] op_sel_hi:[1,0,1]
	s_waitcnt lgkmcnt(3)
	v_mov_b32_e32 v88, v245
	v_pk_add_f32 v[84:85], v[84:85], v[86:87]
	v_pk_mul_f32 v[86:87], v[160:161], v[242:243]
	s_nop 0
	v_pk_fma_f32 v[86:87], v[162:163], v[242:243], v[86:87] op_sel:[0,0,1] op_sel_hi:[1,1,0]
	s_nop 0
	v_pk_fma_f32 v[86:87], v[38:39], v[244:245], v[86:87] op_sel_hi:[1,0,1]
	s_nop 0
	v_pk_fma_f32 v[86:87], v[40:41], v[88:89], v[86:87] op_sel_hi:[1,0,1]
	s_waitcnt lgkmcnt(2)
	v_mov_b32_e32 v88, v249
	v_pk_add_f32 v[84:85], v[84:85], v[86:87]
	v_pk_mul_f32 v[86:87], v[166:167], v[246:247]
	s_nop 0
	v_pk_fma_f32 v[86:87], v[168:169], v[246:247], v[86:87] op_sel:[0,0,1] op_sel_hi:[1,1,0]
	s_nop 0
	v_pk_fma_f32 v[86:87], v[164:165], v[248:249], v[86:87] op_sel_hi:[1,0,1]
	s_nop 0
	v_pk_fma_f32 v[86:87], v[46:47], v[88:89], v[86:87] op_sel_hi:[1,0,1]
	s_waitcnt lgkmcnt(0)
	v_mov_b32_e32 v88, v253
	v_pk_add_f32 v[84:85], v[84:85], v[86:87]
	v_pk_mul_f32 v[86:87], v[170:171], v[80:81]
	s_nop 0
	v_pk_fma_f32 v[80:81], v[172:173], v[80:81], v[86:87] op_sel:[0,0,1] op_sel_hi:[1,1,0]
	s_nop 0
	v_pk_fma_f32 v[80:81], v[48:49], v[82:83], v[80:81] op_sel_hi:[1,0,1]
	v_mov_b32_e32 v82, v83
	v_pk_fma_f32 v[80:81], v[50:51], v[82:83], v[80:81] op_sel_hi:[1,0,1]
	v_pk_mul_f32 v[82:83], v[176:177], v[250:251]
	v_pk_add_f32 v[80:81], v[84:85], v[80:81]
	v_pk_fma_f32 v[82:83], v[178:179], v[250:251], v[82:83] op_sel:[0,0,1] op_sel_hi:[1,1,0]
	s_nop 0
	v_pk_fma_f32 v[86:87], v[174:175], v[252:253], v[82:83] op_sel_hi:[1,0,1]
	ds_read_b128 v[82:85], v196
	v_pk_fma_f32 v[86:87], v[56:57], v[88:89], v[86:87] op_sel_hi:[1,0,1]
	s_nop 0
	v_pk_add_f32 v[80:81], v[80:81], v[86:87]
	ds_read_b128 v[86:89], v197
	s_waitcnt lgkmcnt(1)
	v_pk_mul_f32 v[230:231], v[144:145], v[82:83]
	ds_read_b128 v[234:237], v198
	ds_read_b128 v[238:241], v199
	ds_read_b128 v[242:245], v200
	ds_read_b128 v[246:249], v201
	v_pk_fma_f32 v[82:83], v[6:7], v[82:83], v[230:231] op_sel:[0,0,1] op_sel_hi:[1,1,0]
	s_waitcnt lgkmcnt(4)
	v_mov_b32_e32 v92, v89
	v_pk_fma_f32 v[82:83], v[142:143], v[84:85], v[82:83] op_sel_hi:[1,0,1]
	v_mov_b32_e32 v84, v85
	v_pk_fma_f32 v[230:231], v[140:141], v[84:85], v[82:83] op_sel_hi:[1,0,1]
	v_pk_mul_f32 v[82:83], v[148:149], v[86:87]
	v_pk_add_f32 v[230:231], v[230:231], 0 op_sel_hi:[1,0]
	v_pk_fma_f32 v[82:83], v[150:151], v[86:87], v[82:83] op_sel:[0,0,1] op_sel_hi:[1,1,0]
	s_nop 0
	v_pk_fma_f32 v[250:251], v[146:147], v[88:89], v[82:83] op_sel_hi:[1,0,1]
	ds_read_b128 v[82:85], v202
	ds_read_b128 v[86:89], v203
	v_pk_fma_f32 v[250:251], v[28:29], v[92:93], v[250:251] op_sel_hi:[1,0,1]
	s_waitcnt lgkmcnt(5)
	v_mov_b32_e32 v92, v237
	v_pk_add_f32 v[230:231], v[230:231], v[250:251]
	v_pk_mul_f32 v[250:251], v[152:153], v[234:235]
	s_nop 0
	v_pk_fma_f32 v[234:235], v[154:155], v[234:235], v[250:251] op_sel:[0,0,1] op_sel_hi:[1,1,0]
	s_nop 0
	v_pk_fma_f32 v[234:235], v[30:31], v[236:237], v[234:235] op_sel_hi:[1,0,1]
	s_nop 0
	v_pk_fma_f32 v[234:235], v[32:33], v[92:93], v[234:235] op_sel_hi:[1,0,1]
	s_waitcnt lgkmcnt(4)
	v_mov_b32_e32 v92, v241
	v_pk_add_f32 v[230:231], v[230:231], v[234:235]
	v_pk_mul_f32 v[234:235], v[156:157], v[238:239]
	s_nop 0
	v_pk_fma_f32 v[234:235], v[158:159], v[238:239], v[234:235] op_sel:[0,0,1] op_sel_hi:[1,1,0]
	s_nop 0
	v_pk_fma_f32 v[234:235], v[34:35], v[240:241], v[234:235] op_sel_hi:[1,0,1]
	s_nop 0
	v_pk_fma_f32 v[234:235], v[36:37], v[92:93], v[234:235] op_sel_hi:[1,0,1]
	s_waitcnt lgkmcnt(3)
	v_mov_b32_e32 v92, v245
	v_pk_add_f32 v[230:231], v[230:231], v[234:235]
	v_pk_mul_f32 v[234:235], v[160:161], v[242:243]
	s_nop 0
	v_pk_fma_f32 v[234:235], v[162:163], v[242:243], v[234:235] op_sel:[0,0,1] op_sel_hi:[1,1,0]
	s_nop 0
	v_pk_fma_f32 v[234:235], v[38:39], v[244:245], v[234:235] op_sel_hi:[1,0,1]
	s_nop 0
	v_pk_fma_f32 v[234:235], v[40:41], v[92:93], v[234:235] op_sel_hi:[1,0,1]
	s_waitcnt lgkmcnt(2)
	v_mov_b32_e32 v92, v249
	v_pk_add_f32 v[230:231], v[230:231], v[234:235]
	v_pk_mul_f32 v[234:235], v[166:167], v[246:247]
	s_nop 0
	v_pk_fma_f32 v[234:235], v[168:169], v[246:247], v[234:235] op_sel:[0,0,1] op_sel_hi:[1,1,0]
	s_nop 0
	v_pk_fma_f32 v[234:235], v[164:165], v[248:249], v[234:235] op_sel_hi:[1,0,1]
	s_nop 0
	v_pk_fma_f32 v[234:235], v[46:47], v[92:93], v[234:235] op_sel_hi:[1,0,1]
	s_nop 0
	v_pk_add_f32 v[230:231], v[230:231], v[234:235]
	s_waitcnt lgkmcnt(1)
	v_pk_mul_f32 v[234:235], v[170:171], v[82:83]
	s_nop 0
	v_pk_fma_f32 v[82:83], v[172:173], v[82:83], v[234:235] op_sel:[0,0,1] op_sel_hi:[1,1,0]
	ds_read_b128 v[234:237], v205
	v_pk_fma_f32 v[82:83], v[48:49], v[84:85], v[82:83] op_sel_hi:[1,0,1]
	v_mov_b32_e32 v84, v85
	v_pk_fma_f32 v[82:83], v[50:51], v[84:85], v[82:83] op_sel_hi:[1,0,1]
	s_waitcnt lgkmcnt(1)
	v_pk_mul_f32 v[84:85], v[176:177], v[86:87]
	v_pk_add_f32 v[82:83], v[230:231], v[82:83]
	v_pk_fma_f32 v[84:85], v[178:179], v[86:87], v[84:85] op_sel:[0,0,1] op_sel_hi:[1,1,0]
	s_nop 0
	v_pk_fma_f32 v[230:231], v[174:175], v[88:89], v[84:85] op_sel_hi:[1,0,1]
	ds_read_b128 v[84:87], v204
	v_mov_b32_e32 v88, v89
	v_pk_fma_f32 v[88:89], v[56:57], v[88:89], v[230:231] op_sel_hi:[1,0,1]
	ds_read_b128 v[238:241], v206
	ds_read_b128 v[242:245], v207
	ds_read_b128 v[246:249], v208
	ds_read_b128 v[250:253], v209
	v_pk_add_f32 v[82:83], v[82:83], v[88:89]
	s_waitcnt lgkmcnt(4)
	v_pk_mul_f32 v[88:89], v[144:145], v[84:85]
	s_waitcnt lgkmcnt(3)
	v_mov_b32_e32 v92, v241
	v_pk_fma_f32 v[84:85], v[6:7], v[84:85], v[88:89] op_sel:[0,0,1] op_sel_hi:[1,1,0]
	s_nop 0
	v_pk_fma_f32 v[84:85], v[142:143], v[86:87], v[84:85] op_sel_hi:[1,0,1]
	v_mov_b32_e32 v86, v87
	v_pk_fma_f32 v[88:89], v[140:141], v[86:87], v[84:85] op_sel_hi:[1,0,1]
	v_pk_mul_f32 v[84:85], v[148:149], v[234:235]
	v_mov_b32_e32 v86, v237
	v_pk_fma_f32 v[84:85], v[150:151], v[234:235], v[84:85] op_sel:[0,0,1] op_sel_hi:[1,1,0]
	v_pk_add_f32 v[88:89], v[88:89], 0 op_sel_hi:[1,0]
	v_pk_fma_f32 v[84:85], v[146:147], v[236:237], v[84:85] op_sel_hi:[1,0,1]
	s_nop 0
	v_pk_fma_f32 v[230:231], v[28:29], v[86:87], v[84:85] op_sel_hi:[1,0,1]
	ds_read_b128 v[84:87], v210
	ds_read_b128 v[234:237], v211
	v_pk_add_f32 v[88:89], v[88:89], v[230:231]
	v_pk_mul_f32 v[230:231], v[152:153], v[238:239]
	s_nop 0
	v_pk_fma_f32 v[230:231], v[154:155], v[238:239], v[230:231] op_sel:[0,0,1] op_sel_hi:[1,1,0]
	s_nop 0
	v_pk_fma_f32 v[230:231], v[30:31], v[240:241], v[230:231] op_sel_hi:[1,0,1]
	s_nop 0
	v_pk_fma_f32 v[230:231], v[32:33], v[92:93], v[230:231] op_sel_hi:[1,0,1]
	s_waitcnt lgkmcnt(4)
	v_mov_b32_e32 v92, v245
	v_pk_add_f32 v[88:89], v[88:89], v[230:231]
	v_pk_mul_f32 v[230:231], v[156:157], v[242:243]
	s_nop 0
	v_pk_fma_f32 v[230:231], v[158:159], v[242:243], v[230:231] op_sel:[0,0,1] op_sel_hi:[1,1,0]
	s_nop 0
	v_pk_fma_f32 v[230:231], v[34:35], v[244:245], v[230:231] op_sel_hi:[1,0,1]
	s_nop 0
	v_pk_fma_f32 v[230:231], v[36:37], v[92:93], v[230:231] op_sel_hi:[1,0,1]
	s_waitcnt lgkmcnt(3)
	v_mov_b32_e32 v92, v249
	v_pk_add_f32 v[88:89], v[88:89], v[230:231]
	v_pk_mul_f32 v[230:231], v[160:161], v[246:247]
	s_nop 0
	v_pk_fma_f32 v[230:231], v[162:163], v[246:247], v[230:231] op_sel:[0,0,1] op_sel_hi:[1,1,0]
	s_nop 0
	v_pk_fma_f32 v[230:231], v[38:39], v[248:249], v[230:231] op_sel_hi:[1,0,1]
	s_nop 0
	v_pk_fma_f32 v[230:231], v[40:41], v[92:93], v[230:231] op_sel_hi:[1,0,1]
	s_waitcnt lgkmcnt(2)
	v_mov_b32_e32 v92, v253
	v_pk_add_f32 v[88:89], v[88:89], v[230:231]
	v_pk_mul_f32 v[230:231], v[166:167], v[250:251]
	s_nop 0
	v_pk_fma_f32 v[230:231], v[168:169], v[250:251], v[230:231] op_sel:[0,0,1] op_sel_hi:[1,1,0]
	s_nop 0
	v_pk_fma_f32 v[230:231], v[164:165], v[252:253], v[230:231] op_sel_hi:[1,0,1]
	s_nop 0
	v_pk_fma_f32 v[230:231], v[46:47], v[92:93], v[230:231] op_sel_hi:[1,0,1]
	s_waitcnt lgkmcnt(0)
	v_mov_b32_e32 v92, v237
	v_pk_add_f32 v[88:89], v[88:89], v[230:231]
	v_pk_mul_f32 v[230:231], v[170:171], v[84:85]
	s_nop 0
	v_pk_fma_f32 v[84:85], v[172:173], v[84:85], v[230:231] op_sel:[0,0,1] op_sel_hi:[1,1,0]
	s_nop 0
	v_pk_fma_f32 v[84:85], v[48:49], v[86:87], v[84:85] op_sel_hi:[1,0,1]
	v_mov_b32_e32 v86, v87
	v_pk_fma_f32 v[84:85], v[50:51], v[86:87], v[84:85] op_sel_hi:[1,0,1]
	s_nop 0
	v_pk_add_f32 v[88:89], v[88:89], v[84:85]
	v_pk_mul_f32 v[84:85], v[176:177], v[234:235]
	s_nop 0
	v_pk_fma_f32 v[84:85], v[178:179], v[234:235], v[84:85] op_sel:[0,0,1] op_sel_hi:[1,1,0]
	s_nop 0
	v_pk_fma_f32 v[230:231], v[174:175], v[236:237], v[84:85] op_sel_hi:[1,0,1]
	ds_read_b128 v[84:87], v212
	ds_read_b128 v[234:237], v213
	v_pk_fma_f32 v[230:231], v[56:57], v[92:93], v[230:231] op_sel_hi:[1,0,1]
	ds_read_b128 v[238:241], v214
	ds_read_b128 v[242:245], v215
	ds_read_b128 v[246:249], v216
	ds_read_b128 v[250:253], v217
	v_pk_add_f32 v[88:89], v[88:89], v[230:231]
	s_waitcnt lgkmcnt(5)
	v_pk_mul_f32 v[230:231], v[144:145], v[84:85]
	s_waitcnt lgkmcnt(4)
	v_mov_b32_e32 v92, v237
	v_pk_fma_f32 v[84:85], v[6:7], v[84:85], v[230:231] op_sel:[0,0,1] op_sel_hi:[1,1,0]
	s_nop 0
	v_pk_fma_f32 v[84:85], v[142:143], v[86:87], v[84:85] op_sel_hi:[1,0,1]
	v_mov_b32_e32 v86, v87
	v_pk_fma_f32 v[84:85], v[140:141], v[86:87], v[84:85] op_sel_hi:[1,0,1]
	v_pk_mul_f32 v[86:87], v[148:149], v[234:235]
	v_pk_add_f32 v[84:85], v[84:85], 0 op_sel_hi:[1,0]
	v_pk_fma_f32 v[86:87], v[150:151], v[234:235], v[86:87] op_sel:[0,0,1] op_sel_hi:[1,1,0]
	s_nop 0
	v_pk_fma_f32 v[86:87], v[146:147], v[236:237], v[86:87] op_sel_hi:[1,0,1]
	s_nop 0
	v_pk_fma_f32 v[86:87], v[28:29], v[92:93], v[86:87] op_sel_hi:[1,0,1]
	s_waitcnt lgkmcnt(3)
	v_mov_b32_e32 v92, v241
	v_pk_add_f32 v[230:231], v[84:85], v[86:87]
	v_pk_mul_f32 v[84:85], v[152:153], v[238:239]
	s_nop 0
	v_pk_fma_f32 v[84:85], v[154:155], v[238:239], v[84:85] op_sel:[0,0,1] op_sel_hi:[1,1,0]
	s_nop 0
	v_pk_fma_f32 v[238:239], v[30:31], v[240:241], v[84:85] op_sel_hi:[1,0,1]
	ds_read_b128 v[84:87], v218
	ds_read_b128 v[234:237], v219
	v_pk_fma_f32 v[238:239], v[32:33], v[92:93], v[238:239] op_sel_hi:[1,0,1]
	s_waitcnt lgkmcnt(4)
	v_mov_b32_e32 v92, v245
	v_pk_add_f32 v[230:231], v[230:231], v[238:239]
	v_pk_mul_f32 v[238:239], v[156:157], v[242:243]
	s_nop 0
	v_pk_fma_f32 v[238:239], v[158:159], v[242:243], v[238:239] op_sel:[0,0,1] op_sel_hi:[1,1,0]
	s_nop 0
	v_pk_fma_f32 v[238:239], v[34:35], v[244:245], v[238:239] op_sel_hi:[1,0,1]
	s_nop 0
	v_pk_fma_f32 v[238:239], v[36:37], v[92:93], v[238:239] op_sel_hi:[1,0,1]
	s_waitcnt lgkmcnt(3)
	v_mov_b32_e32 v92, v249
	v_pk_add_f32 v[230:231], v[230:231], v[238:239]
	v_pk_mul_f32 v[238:239], v[160:161], v[246:247]
	s_nop 0
	v_pk_fma_f32 v[238:239], v[162:163], v[246:247], v[238:239] op_sel:[0,0,1] op_sel_hi:[1,1,0]
	s_nop 0
	v_pk_fma_f32 v[238:239], v[38:39], v[248:249], v[238:239] op_sel_hi:[1,0,1]
	s_nop 0
	v_pk_fma_f32 v[238:239], v[40:41], v[92:93], v[238:239] op_sel_hi:[1,0,1]
	s_waitcnt lgkmcnt(2)
	v_mov_b32_e32 v92, v253
	v_pk_add_f32 v[230:231], v[230:231], v[238:239]
	v_pk_mul_f32 v[238:239], v[166:167], v[250:251]
	s_nop 0
	v_pk_fma_f32 v[238:239], v[168:169], v[250:251], v[238:239] op_sel:[0,0,1] op_sel_hi:[1,1,0]
	s_nop 0
	v_pk_fma_f32 v[238:239], v[164:165], v[252:253], v[238:239] op_sel_hi:[1,0,1]
	s_nop 0
	v_pk_fma_f32 v[238:239], v[46:47], v[92:93], v[238:239] op_sel_hi:[1,0,1]
	s_waitcnt lgkmcnt(0)
	v_mov_b32_e32 v92, v237
	v_pk_add_f32 v[230:231], v[230:231], v[238:239]
	v_pk_mul_f32 v[238:239], v[170:171], v[84:85]
	s_nop 0
	v_pk_fma_f32 v[84:85], v[172:173], v[84:85], v[238:239] op_sel:[0,0,1] op_sel_hi:[1,1,0]
	s_nop 0
	v_pk_fma_f32 v[84:85], v[48:49], v[86:87], v[84:85] op_sel_hi:[1,0,1]
	v_mov_b32_e32 v86, v87
	v_pk_fma_f32 v[84:85], v[50:51], v[86:87], v[84:85] op_sel_hi:[1,0,1]
	s_nop 0
	v_pk_add_f32 v[230:231], v[230:231], v[84:85]
	v_pk_mul_f32 v[84:85], v[176:177], v[234:235]
	s_nop 0
	v_pk_fma_f32 v[84:85], v[178:179], v[234:235], v[84:85] op_sel:[0,0,1] op_sel_hi:[1,1,0]
	s_nop 0
	v_pk_fma_f32 v[234:235], v[174:175], v[236:237], v[84:85] op_sel_hi:[1,0,1]
	ds_read_b128 v[84:87], v220
	v_pk_fma_f32 v[234:235], v[56:57], v[92:93], v[234:235] op_sel_hi:[1,0,1]
	s_nop 0
	v_pk_add_f32 v[230:231], v[230:231], v[234:235]
	ds_read_b128 v[234:237], v221
	s_waitcnt lgkmcnt(1)
	v_pk_mul_f32 v[144:145], v[144:145], v[84:85]
	v_mov_b32_e32 v92, v87
	v_pk_fma_f32 v[6:7], v[6:7], v[84:85], v[144:145] op_sel:[0,0,1] op_sel_hi:[1,1,0]
	ds_read_b128 v[238:241], v222
	ds_read_b128 v[242:245], v223
	ds_read_b128 v[246:249], v224
	ds_read_b128 v[250:253], v225
	v_pk_fma_f32 v[6:7], v[142:143], v[86:87], v[6:7] op_sel_hi:[1,0,1]
	ds_read_b128 v[84:87], v226
	ds_read_b128 v[142:145], v227
	v_pk_fma_f32 v[6:7], v[140:141], v[92:93], v[6:7] op_sel_hi:[1,0,1]
	s_waitcnt lgkmcnt(6)
	v_pk_mul_f32 v[140:141], v[148:149], v[234:235]
	v_mov_b32_e32 v92, v237
	v_pk_fma_f32 v[140:141], v[150:151], v[234:235], v[140:141] op_sel:[0,0,1] op_sel_hi:[1,1,0]
	v_pk_add_f32 v[6:7], v[6:7], 0 op_sel_hi:[1,0]
	v_pk_fma_f32 v[140:141], v[146:147], v[236:237], v[140:141] op_sel_hi:[1,0,1]
	s_nop 0
	v_pk_fma_f32 v[28:29], v[28:29], v[92:93], v[140:141] op_sel_hi:[1,0,1]
	s_nop 0
	v_pk_add_f32 v[6:7], v[6:7], v[28:29]
	s_waitcnt lgkmcnt(5)
	v_pk_mul_f32 v[28:29], v[152:153], v[238:239]
	s_nop 0
	v_pk_fma_f32 v[28:29], v[154:155], v[238:239], v[28:29] op_sel:[0,0,1] op_sel_hi:[1,1,0]
	s_nop 0
	v_pk_fma_f32 v[28:29], v[30:31], v[240:241], v[28:29] op_sel_hi:[1,0,1]
	v_mov_b32_e32 v30, v241
	v_pk_fma_f32 v[28:29], v[32:33], v[30:31], v[28:29] op_sel_hi:[1,0,1]
	s_waitcnt lgkmcnt(4)
	v_mov_b32_e32 v30, v245
	v_pk_add_f32 v[6:7], v[6:7], v[28:29]
	v_pk_mul_f32 v[28:29], v[156:157], v[242:243]
	v_cndmask_b32_e64 v32, v63, v79, s[4:5]
	v_pk_fma_f32 v[28:29], v[158:159], v[242:243], v[28:29] op_sel:[0,0,1] op_sel_hi:[1,1,0]
	v_cndmask_b32_e64 v33, v62, v78, s[4:5]
	v_pk_fma_f32 v[28:29], v[34:35], v[244:245], v[28:29] op_sel_hi:[1,0,1]
	ds_bpermute_b32 v32, v180, v32
	v_pk_fma_f32 v[28:29], v[36:37], v[30:31], v[28:29] op_sel_hi:[1,0,1]
	s_waitcnt lgkmcnt(4)
	v_mov_b32_e32 v30, v249
	v_pk_add_f32 v[6:7], v[6:7], v[28:29]
	v_pk_mul_f32 v[28:29], v[160:161], v[246:247]
	ds_bpermute_b32 v33, v180, v33
	v_pk_fma_f32 v[28:29], v[162:163], v[246:247], v[28:29] op_sel:[0,0,1] op_sel_hi:[1,1,0]
	v_cndmask_b32_e64 v34, v65, v81, s[4:5]
	v_pk_fma_f32 v[28:29], v[38:39], v[248:249], v[28:29] op_sel_hi:[1,0,1]
	v_cndmask_b32_e64 v35, v64, v80, s[4:5]
	v_pk_fma_f32 v[28:29], v[40:41], v[30:31], v[28:29] op_sel_hi:[1,0,1]
	s_waitcnt lgkmcnt(4)
	v_mov_b32_e32 v30, v253
	v_pk_add_f32 v[6:7], v[6:7], v[28:29]
	v_pk_mul_f32 v[28:29], v[166:167], v[250:251]
	ds_bpermute_b32 v34, v180, v34
	v_pk_fma_f32 v[28:29], v[168:169], v[250:251], v[28:29] op_sel:[0,0,1] op_sel_hi:[1,1,0]
	ds_bpermute_b32 v35, v180, v35
	v_pk_fma_f32 v[28:29], v[164:165], v[252:253], v[28:29] op_sel_hi:[1,0,1]
	v_cndmask_b32_e64 v36, v67, v83, s[4:5]
	v_pk_fma_f32 v[28:29], v[46:47], v[30:31], v[28:29] op_sel_hi:[1,0,1]
	s_waitcnt lgkmcnt(5)
	v_mov_b32_e32 v30, v87
	v_pk_add_f32 v[6:7], v[6:7], v[28:29]
	v_pk_mul_f32 v[28:29], v[170:171], v[84:85]
	v_cndmask_b32_e64 v37, v66, v82, s[4:5]
	v_pk_fma_f32 v[28:29], v[172:173], v[84:85], v[28:29] op_sel:[0,0,1] op_sel_hi:[1,1,0]
	ds_bpermute_b32 v36, v180, v36
	v_pk_fma_f32 v[28:29], v[48:49], v[86:87], v[28:29] op_sel_hi:[1,0,1]
	ds_bpermute_b32 v37, v180, v37
	v_pk_fma_f32 v[28:29], v[50:51], v[30:31], v[28:29] op_sel_hi:[1,0,1]
	s_waitcnt lgkmcnt(6)
	v_mov_b32_e32 v30, v145
	v_pk_add_f32 v[6:7], v[6:7], v[28:29]
	v_pk_mul_f32 v[28:29], v[176:177], v[142:143]
	v_cndmask_b32_e64 v38, v69, v89, s[4:5]
	v_pk_fma_f32 v[28:29], v[178:179], v[142:143], v[28:29] op_sel:[0,0,1] op_sel_hi:[1,1,0]
	v_cndmask_b32_e64 v39, v68, v88, s[4:5]
	v_pk_fma_f32 v[28:29], v[174:175], v[144:145], v[28:29] op_sel_hi:[1,0,1]
	v_cndmask_b32_e64 v49, v74, v58, s[4:5]
	v_pk_fma_f32 v[28:29], v[56:57], v[30:31], v[28:29] op_sel_hi:[1,0,1]
	v_cndmask_b32_e64 v30, v61, v77, s[4:5]
	v_pk_add_f32 v[6:7], v[6:7], v[28:29]
	v_cndmask_b32_e64 v28, v59, v75, s[4:5]
	v_cndmask_b32_e64 v29, v58, v74, s[4:5]
	ds_bpermute_b32 v28, v180, v28
	ds_bpermute_b32 v29, v180, v29
	v_cndmask_b32_e64 v31, v60, v76, s[4:5]
	ds_bpermute_b32 v30, v180, v30
	ds_bpermute_b32 v31, v180, v31
	v_cndmask_b32_e64 v48, v75, v59, s[4:5]
	ds_bpermute_b32 v38, v180, v38
	ds_bpermute_b32 v39, v180, v39
	v_cndmask_b32_e64 v40, v71, v231, s[4:5]
	v_cndmask_b32_e64 v41, v70, v230, s[4:5]
	s_waitcnt lgkmcnt(4)
	v_pk_add_f32 v[28:29], v[48:49], v[28:29]
	v_cndmask_b32_e64 v49, v76, v60, s[4:5]
	v_cndmask_b32_e64 v48, v77, v61, s[4:5]
	ds_bpermute_b32 v40, v180, v40
	ds_bpermute_b32 v41, v180, v41
	v_cndmask_b32_e64 v46, v73, v7, s[4:5]
	v_cndmask_b32_e64 v47, v72, v6, s[4:5]
	s_waitcnt lgkmcnt(4)
	v_pk_add_f32 v[30:31], v[48:49], v[30:31]
	v_cndmask_b32_e64 v49, v78, v62, s[4:5]
	v_cndmask_b32_e64 v48, v79, v63, s[4:5]
	ds_bpermute_b32 v46, v180, v46
	ds_bpermute_b32 v47, v180, v47
	v_pk_add_f32 v[32:33], v[48:49], v[32:33]
	v_cndmask_b32_e64 v49, v80, v64, s[4:5]
	v_cndmask_b32_e64 v48, v81, v65, s[4:5]
	v_pk_add_f32 v[34:35], v[48:49], v[34:35]
	v_cndmask_b32_e64 v49, v82, v66, s[4:5]
	v_cndmask_b32_e64 v48, v83, v67, s[4:5]
	v_pk_add_f32 v[36:37], v[48:49], v[36:37]
	v_cndmask_b32_e64 v49, v88, v68, s[4:5]
	v_cndmask_b32_e64 v48, v89, v69, s[4:5]
	s_waitcnt lgkmcnt(4)
	v_pk_add_f32 v[38:39], v[48:49], v[38:39]
	v_cndmask_b32_e64 v49, v230, v70, s[4:5]
	v_cndmask_b32_e64 v48, v231, v71, s[4:5]
	s_waitcnt lgkmcnt(2)
	v_pk_add_f32 v[40:41], v[48:49], v[40:41]
	v_cndmask_b32_e64 v49, v6, v72, s[4:5]
	v_cndmask_b32_e64 v48, v7, v73, s[4:5]
	s_waitcnt lgkmcnt(0)
	v_pk_add_f32 v[6:7], v[48:49], v[46:47]
	v_cndmask_b32_e64 v46, v28, v36, s[10:11]
	v_cndmask_b32_e64 v49, v37, v29, s[10:11]
	v_cndmask_b32_e64 v29, v29, v37, s[10:11]
	ds_bpermute_b32 v46, v181, v46
	ds_bpermute_b32 v47, v181, v29
	v_cndmask_b32_e64 v29, v30, v38, s[10:11]
	ds_bpermute_b32 v50, v181, v29
	v_cndmask_b32_e64 v29, v31, v39, s[10:11]
	v_cndmask_b32_e64 v31, v39, v31, s[10:11]
	v_cndmask_b32_e64 v39, v41, v33, s[10:11]
	v_cndmask_b32_e64 v33, v33, v41, s[10:11]
	v_cndmask_b32_e64 v48, v36, v28, s[10:11]
	v_cndmask_b32_e64 v36, v32, v40, s[10:11]
	ds_bpermute_b32 v37, v181, v33
	v_cndmask_b32_e64 v33, v34, v6, s[10:11]
	ds_bpermute_b32 v51, v181, v29
	s_waitcnt lgkmcnt(3)
	v_pk_add_f32 v[28:29], v[48:49], v[46:47]
	ds_bpermute_b32 v36, v181, v36
	ds_bpermute_b32 v46, v181, v33
	v_cndmask_b32_e64 v33, v35, v7, s[10:11]
	ds_bpermute_b32 v47, v181, v33
	v_cndmask_b32_e64 v30, v38, v30, s[10:11]
	v_cndmask_b32_e64 v38, v40, v32, s[10:11]
	s_waitcnt lgkmcnt(2)
	v_pk_add_f32 v[32:33], v[38:39], v[36:37]
	v_cndmask_b32_e64 v7, v7, v35, s[10:11]
	v_cndmask_b32_e64 v6, v6, v34, s[10:11]
	v_pk_add_f32 v[30:31], v[30:31], v[50:51]
	s_waitcnt lgkmcnt(0)
	v_pk_add_f32 v[6:7], v[6:7], v[46:47]
	v_cndmask_b32_e64 v37, v33, v29, s[12:13]
	v_cndmask_b32_e64 v29, v29, v33, s[12:13]
	s_nop 1
	v_mov_b32_dpp v35, v29 row_ror:8 row_mask:0xf bank_mask:0xf
	v_cndmask_b32_e64 v29, v30, v6, s[12:13]
	v_cndmask_b32_e64 v34, v28, v32, s[12:13]
	s_nop 1
	v_mov_b32_dpp v38, v29 row_ror:8 row_mask:0xf bank_mask:0xf
	v_cndmask_b32_e64 v29, v31, v7, s[12:13]
	s_nop 1
	v_mov_b32_dpp v34, v34 row_ror:8 row_mask:0xf bank_mask:0xf
	s_nop 1
	v_mov_b32_dpp v39, v29 row_ror:8 row_mask:0xf bank_mask:0xf
	v_cndmask_b32_e64 v36, v32, v28, s[12:13]
	v_cndmask_b32_e64 v7, v7, v31, s[12:13]
	v_cndmask_b32_e64 v6, v6, v30, s[12:13]
	s_waitcnt lgkmcnt(1)
	v_pk_add_f32 v[28:29], v[36:37], v[34:35]
	s_waitcnt lgkmcnt(0)
	v_pk_add_f32 v[6:7], v[6:7], v[38:39]
	s_nop 0
	v_cndmask_b32_e64 v30, v28, v6, s[14:15]
	v_cndmask_b32_e64 v31, v29, v7, s[14:15]
	ds_bpermute_b32 v30, v183, v30
	ds_bpermute_b32 v31, v183, v31
	v_cndmask_b32_e64 v7, v7, v29, s[14:15]
	v_cndmask_b32_e64 v6, v6, v28, s[14:15]
	s_waitcnt lgkmcnt(0)
	v_pk_add_f32 v[6:7], v[6:7], v[30:31]
	s_nop 1
	v_mov_b32_dpp v28, v6 quad_perm:[2,3,0,1] row_mask:0xf bank_mask:0xf
	s_nop 1
	v_mov_b32_dpp v29, v7 quad_perm:[2,3,0,1] row_mask:0xf bank_mask:0xf
	s_waitcnt lgkmcnt(0)
	v_pk_add_f32 v[6:7], v[6:7], v[28:29]
	s_nop 1
	v_mov_b32_dpp v28, v6 quad_perm:[1,0,3,2] row_mask:0xf bank_mask:0xf
	s_nop 1
	v_mov_b32_dpp v29, v7 quad_perm:[1,0,3,2] row_mask:0xf bank_mask:0xf
	s_and_saveexec_b64 s[0:1], s[2:3]
	s_cbranch_execz .LBB0_82
	global_load_dword v30, v[106:107], off
	s_waitcnt lgkmcnt(0)
	v_pk_add_f32 v[6:7], v[6:7], v[28:29]
	s_waitcnt vmcnt(0)
	v_pk_add_f32 v[6:7], v[6:7], v[30:31] op_sel_hi:[1,0]
	s_and_saveexec_b64 s[42:43], s[6:7]
	s_cbranch_execz .LBB0_80
	v_mul_f32_e64 v28, |v6|, s66
	v_exp_f32_e32 v64, v28
	v_max_f32_e32 v6, v6, v6
	v_min_f32_e32 v6, 0, v6
	v_add_f32_e32 v30, 1.0, v64
	v_add_f32_e32 v28, -1.0, v30
	v_sub_f32_e32 v29, v28, v30
	v_sub_f32_e32 v28, v64, v28
	v_add_f32_e32 v29, 1.0, v29
	v_add_f32_e32 v31, v28, v29
	v_frexp_mant_f32_e32 v32, v30
	v_cvt_f64_f32_e32 v[28:29], v30
	v_frexp_exp_i32_f64_e32 v28, v[28:29]
	v_cmp_gt_f32_e32 vcc, s67, v32
	s_nop 1
	v_subbrev_co_u32_e32 v56, vcc, 0, v28, vcc
	v_sub_u32_e32 v29, 0, v56
	v_ldexp_f32 v28, v30, v29
	v_mul_f32_e64 v30, |v7|, s66
	v_exp_f32_e32 v65, v30
	v_ldexp_f32 v30, v31, v29
	v_max_f32_e32 v7, v7, v7
	v_min_f32_e32 v7, 0, v7
	v_add_f32_e32 v29, 1.0, v65
	v_add_f32_e32 v31, -1.0, v29
	v_sub_f32_e32 v32, v31, v29
	v_add_f32_e32 v32, 1.0, v32
	v_sub_f32_e32 v31, v65, v31
	v_add_f32_e32 v31, v31, v32
	v_frexp_mant_f32_e32 v34, v29
	v_cvt_f64_f32_e32 v[32:33], v29
	v_frexp_exp_i32_f64_e32 v32, v[32:33]
	v_cmp_gt_f32_e32 vcc, s67, v34
	s_nop 1
	v_subbrev_co_u32_e32 v57, vcc, 0, v32, vcc
	v_sub_u32_e32 v32, 0, v57
	v_ldexp_f32 v29, v29, v32
	v_ldexp_f32 v31, v31, v32
	v_pk_add_f32 v[32:33], v[28:29], 1.0 op_sel_hi:[1,0]
	v_pk_add_f32 v[40:41], v[28:29], -1.0 op_sel_hi:[1,0]
	v_pk_add_f32 v[34:35], v[32:33], -1.0 op_sel_hi:[1,0]
	v_pk_add_f32 v[46:47], v[40:41], 1.0 op_sel_hi:[1,0]
	v_pk_add_f32 v[34:35], v[28:29], v[34:35] neg_lo:[0,1] neg_hi:[0,1]
	v_pk_add_f32 v[28:29], v[28:29], v[46:47] neg_lo:[0,1] neg_hi:[0,1]
	v_pk_add_f32 v[34:35], v[30:31], v[34:35]
	v_pk_add_f32 v[28:29], v[30:31], v[28:29]
	v_pk_add_f32 v[36:37], v[32:33], v[34:35]
	v_pk_add_f32 v[30:31], v[40:41], v[28:29]
	v_rcp_f32_e32 v38, v36
	v_rcp_f32_e32 v39, v37
	v_pk_add_f32 v[32:33], v[36:37], v[32:33] neg_lo:[0,1] neg_hi:[0,1]
	v_pk_add_f32 v[40:41], v[30:31], v[40:41] neg_lo:[0,1] neg_hi:[0,1]
	v_pk_add_f32 v[32:33], v[34:35], v[32:33] neg_lo:[0,1] neg_hi:[0,1]
	v_pk_mul_f32 v[34:35], v[30:31], v[38:39]
	v_pk_add_f32 v[28:29], v[28:29], v[40:41] neg_lo:[0,1] neg_hi:[0,1]
	v_pk_mul_f32 v[40:41], v[36:37], v[34:35]
	v_cmp_neq_f32_e32 vcc, s68, v64
	v_pk_fma_f32 v[46:47], v[34:35], v[36:37], v[40:41] neg_lo:[0,0,1] neg_hi:[0,0,1]
	s_nop 0
	v_pk_fma_f32 v[46:47], v[34:35], v[32:33], v[46:47]
	s_nop 0
	v_pk_add_f32 v[48:49], v[40:41], v[46:47]
	s_nop 0
	v_pk_add_f32 v[50:51], v[30:31], v[48:49] neg_lo:[0,1] neg_hi:[0,1]
	v_pk_add_f32 v[40:41], v[48:49], v[40:41] neg_lo:[0,1] neg_hi:[0,1]
	v_pk_add_f32 v[30:31], v[30:31], v[50:51] neg_lo:[0,1] neg_hi:[0,1]
	s_nop 0
	v_pk_add_f32 v[30:31], v[30:31], v[48:49] neg_lo:[0,1] neg_hi:[0,1]
	s_nop 0
	v_pk_add_f32 v[28:29], v[28:29], v[30:31]
	v_pk_add_f32 v[30:31], v[40:41], v[46:47] neg_lo:[0,1] neg_hi:[0,1]
	s_nop 0
	v_pk_add_f32 v[28:29], v[30:31], v[28:29]
	s_nop 0
	v_pk_add_f32 v[30:31], v[50:51], v[28:29]
	s_nop 0
	v_pk_mul_f32 v[40:41], v[38:39], v[30:31]
	s_nop 0
	v_pk_mul_f32 v[46:47], v[36:37], v[40:41]
	s_nop 0
	v_pk_fma_f32 v[36:37], v[40:41], v[36:37], v[46:47] neg_lo:[0,0,1] neg_hi:[0,0,1]
	s_nop 0
	v_pk_fma_f32 v[32:33], v[40:41], v[32:33], v[36:37]
	v_pk_add_f32 v[36:37], v[50:51], v[30:31] neg_lo:[0,1] neg_hi:[0,1]
	s_nop 0
	v_pk_add_f32 v[28:29], v[28:29], v[36:37]
	v_pk_add_f32 v[36:37], v[46:47], v[32:33]
	s_nop 0
	v_pk_add_f32 v[48:49], v[30:31], v[36:37] neg_lo:[0,1] neg_hi:[0,1]
	v_pk_add_f32 v[46:47], v[36:37], v[46:47] neg_lo:[0,1] neg_hi:[0,1]
	v_pk_add_f32 v[30:31], v[30:31], v[48:49] neg_lo:[0,1] neg_hi:[0,1]
	s_nop 0
	v_pk_add_f32 v[30:31], v[30:31], v[36:37] neg_lo:[0,1] neg_hi:[0,1]
	s_nop 0
	v_pk_add_f32 v[28:29], v[28:29], v[30:31]
	v_pk_add_f32 v[30:31], v[46:47], v[32:33] neg_lo:[0,1] neg_hi:[0,1]
	s_nop 0
	v_pk_add_f32 v[28:29], v[30:31], v[28:29]
	v_pk_add_f32 v[30:31], v[34:35], v[40:41]
	v_pk_add_f32 v[28:29], v[48:49], v[28:29]
	v_pk_add_f32 v[32:33], v[30:31], v[34:35] neg_lo:[0,1] neg_hi:[0,1]
	v_pk_mul_f32 v[28:29], v[38:39], v[28:29]
	v_pk_add_f32 v[32:33], v[40:41], v[32:33] neg_lo:[0,1] neg_hi:[0,1]
	v_cvt_f32_i32_e32 v39, v57
	v_pk_add_f32 v[28:29], v[32:33], v[28:29]
	v_cvt_f32_i32_e32 v38, v56
	v_pk_add_f32 v[32:33], v[30:31], v[28:29]
	s_nop 0
	v_pk_mul_f32 v[34:35], v[32:33], v[32:33]
	v_pk_add_f32 v[30:31], v[32:33], v[30:31] neg_lo:[0,1] neg_hi:[0,1]
	v_pk_fma_f32 v[36:37], v[34:35], s[44:45], v[138:139] op_sel_hi:[1,0,0]
	v_pk_add_f32 v[28:29], v[28:29], v[30:31] neg_lo:[0,1] neg_hi:[0,1]
	v_ldexp_f32 v30, v32, 1
	v_pk_fma_f32 v[36:37], v[34:35], v[36:37], s[50:51] op_sel_hi:[1,1,0]
	v_ldexp_f32 v31, v33, 1
	v_pk_mul_f32 v[32:33], v[32:33], v[34:35]
	v_pk_mul_f32 v[34:35], v[38:39], s[52:53] op_sel_hi:[1,0]
	v_pk_mul_f32 v[32:33], v[32:33], v[36:37]
	v_pk_fma_f32 v[46:47], v[38:39], s[52:53], v[34:35] op_sel_hi:[1,0,1] neg_lo:[0,0,1] neg_hi:[0,0,1]
	v_pk_add_f32 v[36:37], v[30:31], v[32:33]
	v_ldexp_f32 v41, v29, 1
	v_pk_add_f32 v[30:31], v[36:37], v[30:31] neg_lo:[0,1] neg_hi:[0,1]
	v_pk_fma_f32 v[38:39], v[38:39], s[60:61], v[46:47] op_sel_hi:[1,0,1]
	v_pk_add_f32 v[30:31], v[32:33], v[30:31] neg_lo:[0,1] neg_hi:[0,1]
	v_ldexp_f32 v28, v28, 1
	v_mov_b32_e32 v32, v34
	v_mov_b32_e32 v33, v31
	v_mov_b32_e32 v40, v38
	v_mov_b32_e32 v29, v41
	v_pk_add_f32 v[32:33], v[32:33], v[40:41]
	v_pk_add_f32 v[40:41], v[28:29], v[30:31]
	v_mov_b32_e32 v31, v37
	v_mov_b32_e32 v29, v41
	v_pk_add_f32 v[46:47], v[34:35], v[38:39]
	v_pk_add_f32 v[28:29], v[28:29], v[30:31]
	v_pk_add_f32 v[30:31], v[36:37], v[40:41]
	v_mov_b32_e32 v60, v36
	v_pk_add_f32 v[48:49], v[46:47], v[30:31]
	v_mov_b32_e32 v58, v30
	v_mov_b32_e32 v59, v49
	v_mov_b32_e32 v61, v47
	v_pk_add_f32 v[58:59], v[58:59], v[60:61] neg_lo:[0,1] neg_hi:[0,1]
	v_mov_b32_e32 v50, v48
	v_mov_b32_e32 v51, v47
	v_mov_b32_e32 v56, v46
	v_mov_b32_e32 v57, v35
	v_mov_b32_e32 v60, v46
	v_mov_b32_e32 v61, v49
	v_mov_b32_e32 v35, v59
	v_pk_add_f32 v[50:51], v[50:51], v[56:57] neg_lo:[0,1] neg_hi:[0,1]
	v_mov_b32_e32 v56, v30
	v_mov_b32_e32 v57, v39
	v_pk_add_f32 v[34:35], v[60:61], v[34:35] neg_lo:[0,1] neg_hi:[0,1]
	v_pk_add_f32 v[56:57], v[56:57], v[50:51] neg_lo:[0,1] neg_hi:[0,1]
	v_mov_b32_e32 v60, v34
	v_mov_b32_e32 v61, v51
	v_mov_b32_e32 v62, v48
	v_mov_b32_e32 v63, v31
	v_mov_b32_e32 v51, v37
	v_pk_add_f32 v[60:61], v[38:39], v[60:61] neg_lo:[0,1] neg_hi:[0,1]
	v_pk_add_f32 v[50:51], v[62:63], v[50:51] neg_lo:[0,1] neg_hi:[0,1]
	v_mov_b32_e32 v39, v47
	v_pk_add_f32 v[32:33], v[32:33], v[50:51] neg_lo:[0,1] neg_hi:[0,1]
	v_pk_add_f32 v[34:35], v[38:39], v[34:35] neg_lo:[0,1] neg_hi:[0,1]
	v_pk_add_f32 v[28:29], v[28:29], v[58:59] neg_lo:[0,1] neg_hi:[0,1]
	v_pk_add_f32 v[30:31], v[30:31], v[36:37] neg_lo:[0,1] neg_hi:[0,1]
	v_pk_add_f32 v[36:37], v[28:29], v[34:35]
	v_mov_b32_e32 v35, v57
	v_mov_b32_e32 v29, v33
	v_pk_add_f32 v[38:39], v[56:57], v[32:33]
	v_pk_add_f32 v[28:29], v[34:35], v[28:29]
	v_mov_b32_e32 v32, v36
	v_pk_add_f32 v[28:29], v[28:29], v[60:61] neg_lo:[0,1] neg_hi:[0,1]
	v_mov_b32_e32 v33, v39
	v_pk_add_f32 v[30:31], v[40:41], v[30:31] neg_lo:[0,1] neg_hi:[0,1]
	v_pk_add_f32 v[32:33], v[32:33], v[28:29] neg_lo:[0,1] neg_hi:[0,1]
	v_pk_add_f32 v[28:29], v[30:31], v[28:29] neg_lo:[0,1] neg_hi:[0,1]
	v_pk_add_f32 v[32:33], v[34:35], v[32:33] neg_lo:[0,1] neg_hi:[0,1]
	v_pk_add_f32 v[30:31], v[38:39], v[36:37]
	v_pk_add_f32 v[28:29], v[28:29], v[32:33]
	v_pk_add_f32 v[32:33], v[48:49], v[30:31]
	s_nop 0
	v_pk_add_f32 v[34:35], v[32:33], v[48:49] neg_lo:[0,1] neg_hi:[0,1]
	s_nop 0
	v_pk_add_f32 v[30:31], v[30:31], v[34:35] neg_lo:[0,1] neg_hi:[0,1]
	s_nop 0
	v_pk_add_f32 v[28:29], v[28:29], v[30:31]
	s_nop 0
	v_pk_add_f32 v[28:29], v[32:33], v[28:29]
	s_nop 0
	v_cndmask_b32_e32 v28, v229, v28, vcc
	v_cmp_neq_f32_e32 vcc, s68, v65
	s_nop 1
	v_cndmask_b32_e32 v29, v229, v29, vcc
	v_cmp_ngt_f32_e32 vcc, -1.0, v65
	s_nop 1
	v_cndmask_b32_e32 v29, v233, v29, vcc
	v_cmp_ngt_f32_e32 vcc, -1.0, v64
	s_nop 1
	v_cndmask_b32_e32 v28, v233, v28, vcc
	v_cmp_neq_f32_e32 vcc, -1.0, v64
	s_nop 1
	v_cndmask_b32_e32 v28, v254, v28, vcc
	v_cmp_neq_f32_e32 vcc, -1.0, v65
	s_nop 1
	v_cndmask_b32_e32 v29, v254, v29, vcc
	v_cmp_lt_f32_e64 vcc, |v65|, s69
	s_nop 1
	v_cndmask_b32_e32 v29, v29, v65, vcc
	v_cmp_lt_f32_e64 vcc, |v64|, s69
	s_nop 1
	v_cndmask_b32_e32 v28, v28, v64, vcc
	v_pk_add_f32 v[6:7], v[6:7], v[28:29] neg_lo:[0,1] neg_hi:[0,1]

.LBB0_82:
	s_or_b64 exec, exec, s[0:1]
	s_waitcnt vmcnt(4)
	v_max_f32_e64 v6, |v55|, |v55|
	v_max_f32_e64 v7, |v54|, |v54|
	v_max_f32_e32 v6, v7, v6
	v_max_f32_e64 v7, |v45|, |v45|
	s_waitcnt lgkmcnt(1)
	v_max_f32_e64 v28, |v44|, |v44|
	v_max_f32_e32 v7, v28, v7
	v_max3_f32 v6, |v52|, |v53|, v6
	v_max3_f32 v7, |v42|, |v43|, v7
	v_max3_f32 v6, v6, 0, v7
	v_max_f32_e64 v7, |v27|, |v27|
	v_max_f32_e64 v28, |v26|, |v26|
	v_max_f32_e32 v7, v28, v7
	v_max_f32_e64 v28, |v23|, |v23|
	s_waitcnt lgkmcnt(0)
	v_max_f32_e64 v29, |v22|, |v22|
	v_max_f32_e32 v28, v29, v28
	v_max3_f32 v7, |v24|, |v25|, v7
	v_max3_f32 v28, |v20|, |v21|, v28
	v_max3_f32 v6, v6, v7, v28
	s_waitcnt vmcnt(3)
	v_max_f32_e64 v7, |v19|, |v19|
	v_max_f32_e64 v28, |v18|, |v18|
	v_max_f32_e32 v7, v28, v7
	v_max_f32_e64 v28, |v15|, |v15|
	v_max_f32_e64 v29, |v14|, |v14|
	v_max_f32_e32 v28, v29, v28
	v_max3_f32 v7, |v16|, |v17|, v7
	v_max3_f32 v28, |v12|, |v13|, v28
	v_max3_f32 v6, v6, v7, v28
	v_max_f32_e64 v7, |v11|, |v11|
	v_max_f32_e64 v28, |v10|, |v10|
	v_max_f32_e32 v7, v28, v7
	v_max_f32_e64 v28, |v5|, |v5|
	v_max_f32_e64 v29, |v4|, |v4|
	v_max_f32_e32 v28, v29, v28
	v_max3_f32 v7, |v8|, |v9|, v7
	v_max3_f32 v28, |v2|, |v3|, v28
	v_max3_f32 v6, v6, v7, v28
	v_mov_b32_e32 v7, v6
	s_nop 1
	v_permlane32_swap_b32 v7, v6
	s_waitcnt lgkmcnt(0)
	v_max_f32_e32 v7, v7, v7
	v_max_f32_e32 v6, v6, v7
	v_mov_b32_e32 v7, v6
	s_nop 1
	v_permlane16_swap_b32 v7, v6
	s_waitcnt lgkmcnt(0)
	v_max_f32_e32 v7, v7, v7
	v_max_f32_e32 v6, v6, v7
	s_nop 1
	v_mov_b32_dpp v7, v6 row_ror:8 row_mask:0xf bank_mask:0xf
	s_waitcnt lgkmcnt(0)
	v_max_f32_e32 v7, v7, v7
	v_max_f32_e32 v6, v6, v7
	s_nop 1
	v_mov_b32_dpp v7, v6 row_ror:12 row_mask:0xf bank_mask:0x5
	v_mov_b32_dpp v7, v6 row_ror:4 row_mask:0xf bank_mask:0xa
	s_waitcnt lgkmcnt(0)
	v_max_f32_e32 v7, v7, v7
	v_max_f32_e32 v6, v6, v7
	s_nop 1
	v_mov_b32_dpp v7, v6 quad_perm:[2,3,0,1] row_mask:0xf bank_mask:0xf
	s_waitcnt lgkmcnt(0)
	v_max_f32_e32 v7, v7, v7
	v_max_f32_e32 v6, v6, v7
	s_nop 1
	v_mov_b32_dpp v7, v6 quad_perm:[1,0,3,2] row_mask:0xf bank_mask:0xf
	s_waitcnt lgkmcnt(0)
	v_max_f32_e32 v7, v7, v7
	v_max_f32_e32 v32, v6, v7
	v_cmp_lt_f32_e64 s[0:1], 0, v32
	s_and_saveexec_b64 s[42:43], s[20:21]
	s_xor_b64 s[42:43], exec, s[42:43]
	s_cbranch_execz .LBB0_86
	v_mov_b32_e32 v34, 0
	s_and_saveexec_b64 s[62:63], s[0:1]
	s_cbranch_execz .LBB0_85
	v_div_scale_f32 v6, s[86:87], v32, v32, s82
	v_rcp_f32_e32 v7, v6
	v_div_scale_f32 v28, vcc, s82, v32, s82
	v_fma_f32 v29, -v6, v7, 1.0
	v_fmac_f32_e32 v7, v29, v7
	v_mul_f32_e32 v29, v28, v7
	v_fma_f32 v30, -v6, v29, v28
	v_fmac_f32_e32 v29, v30, v7
	v_fma_f32 v6, -v6, v29, v28
	v_div_fmas_f32 v6, v6, v7, v29
	v_div_fixup_f32 v34, v6, v32, s82

.LBB0_122:
	s_or_b64 exec, exec, s[0:1]
	s_and_saveexec_b64 s[20:21], s[16:17]
	s_cbranch_execz .LBB0_60
	v_mov_b32_e32 v2, s55
	v_mov_b32_e32 v3, s57
	v_cmp_lt_i32_e64 s[16:17], s65, v232
	v_and_b32_e32 v38, 0x3fff, v232
	v_mov_b32_e32 v4, s56
	v_cndmask_b32_e64 v3, v2, v3, s[16:17]
	v_mov_b32_e32 v2, s54
	v_cndmask_b32_e64 v2, v2, v4, s[16:17]
	v_lshlrev_b32_e32 v92, 13, v38
	v_lshl_add_u64 v[2:3], v[2:3], 0, v[92:93]
	v_mov_b32_e32 v117, v93
	v_lshl_add_u64 v[2:3], v[2:3], 0, v[116:117]
	v_add_co_u32_e32 v4, vcc, s61, v2
	global_load_dwordx4 v[32:35], v[2:3], off nt
	global_load_dwordx4 v[28:31], v[2:3], off offset:16 nt
	global_load_dwordx4 v[22:25], v[2:3], off offset:32 nt
	global_load_dwordx4 v[18:21], v[2:3], off offset:48 nt
	v_addc_co_u32_e32 v5, vcc, 0, v3, vcc
	global_load_dwordx4 v[14:17], v[4:5], off nt
	v_lshl_add_u64 v[2:3], v[2:3], 0, s[30:31]
	global_load_dwordx4 v[10:13], v[2:3], off offset:16 nt
	global_load_dwordx4 v[6:9], v[2:3], off offset:32 nt
	s_nop 0
	global_load_dwordx4 v[2:5], v[2:3], off offset:48 nt
	v_cmp_gt_i32_e64 s[18:19], s64, v232
	s_waitcnt vmcnt(0)
	v_max_f32_e64 v26, |v35|, |v35|
	v_max_f32_e64 v27, |v34|, |v34|
	s_waitcnt vmcnt(0)
	v_max_f32_e64 v36, |v31|, |v31|
	v_max_f32_e64 v37, |v30|, |v30|
	s_waitcnt vmcnt(0)
	v_max_f32_e64 v39, |v25|, |v25|
	v_max_f32_e64 v40, |v24|, |v24|
	s_waitcnt vmcnt(0)
	v_max_f32_e64 v41, |v21|, |v21|
	v_max_f32_e64 v42, |v20|, |v20|
	v_max_f32_e32 v26, v27, v26
	v_max_f32_e32 v27, v37, v36
	v_max_f32_e32 v36, v40, v39
	v_max_f32_e32 v37, v42, v41
	s_waitcnt vmcnt(0)
	v_max_f32_e64 v39, |v17|, |v17|
	v_max_f32_e64 v40, |v16|, |v16|
	s_waitcnt vmcnt(0)
	v_max_f32_e64 v41, |v13|, |v13|
	v_max_f32_e64 v42, |v12|, |v12|
	v_max3_f32 v26, |v32|, |v33|, v26
	v_max3_f32 v27, |v28|, |v29|, v27
	s_waitcnt vmcnt(0)
	v_max_f32_e64 v43, |v9|, |v9|
	v_max_f32_e64 v44, |v8|, |v8|
	s_waitcnt vmcnt(0)
	v_max_f32_e64 v45, |v5|, |v5|
	v_max_f32_e64 v46, |v4|, |v4|
	v_max3_f32 v36, |v22|, |v23|, v36
	v_max3_f32 v37, |v18|, |v19|, v37
	v_max_f32_e32 v39, v40, v39
	v_max_f32_e32 v40, v42, v41
	v_max3_f32 v26, v26, 0, v27
	v_max_f32_e32 v41, v44, v43
	v_max_f32_e32 v42, v46, v45
	v_max3_f32 v27, |v14|, |v15|, v39
	v_max3_f32 v39, |v10|, |v11|, v40
	v_max3_f32 v26, v26, v36, v37
	v_max3_f32 v40, |v6|, |v7|, v41
	v_max3_f32 v26, v26, v27, v39
	v_max3_f32 v27, |v2|, |v3|, v42
	v_max3_f32 v26, v26, v40, v27
	v_mov_b32_e32 v27, v26
	s_nop 1
	v_permlane32_swap_b32 v27, v26
	s_waitcnt lgkmcnt(0)
	v_max_f32_e32 v27, v27, v27
	v_max_f32_e32 v26, v26, v27
	v_mov_b32_e32 v27, v26
	s_nop 1
	v_permlane16_swap_b32 v27, v26
	s_waitcnt lgkmcnt(0)
	v_max_f32_e32 v27, v27, v27
	v_max_f32_e32 v26, v26, v27
	s_nop 1
	v_mov_b32_dpp v27, v26 row_ror:8 row_mask:0xf bank_mask:0xf
	s_waitcnt lgkmcnt(0)
	v_max_f32_e32 v27, v27, v27
	v_max_f32_e32 v26, v26, v27
	s_nop 1
	v_mov_b32_dpp v27, v26 row_ror:12 row_mask:0xf bank_mask:0x5
	v_mov_b32_dpp v27, v26 row_ror:4 row_mask:0xf bank_mask:0xa
	s_waitcnt lgkmcnt(0)
	v_max_f32_e32 v27, v27, v27
	v_max_f32_e32 v26, v26, v27
	s_nop 1
	v_mov_b32_dpp v27, v26 quad_perm:[2,3,0,1] row_mask:0xf bank_mask:0xf
	s_waitcnt lgkmcnt(0)
	v_max_f32_e32 v27, v27, v27
	v_max_f32_e32 v26, v26, v27
	s_nop 1
	v_mov_b32_dpp v27, v26 quad_perm:[1,0,3,2] row_mask:0xf bank_mask:0xf
	s_waitcnt lgkmcnt(0)
	v_max_f32_e32 v27, v27, v27
	v_max_f32_e32 v39, v26, v27
	v_cmp_lt_f32_e64 s[0:1], 0, v39
	s_and_saveexec_b64 s[42:43], s[18:19]
	s_xor_b64 s[42:43], exec, s[42:43]
	s_cbranch_execz .LBB0_127
	v_mov_b32_e32 v41, 0
	s_and_saveexec_b64 s[62:63], s[0:1]
	s_cbranch_execz .LBB0_126
	v_div_scale_f32 v26, s[86:87], v39, v39, s82
	v_rcp_f32_e32 v27, v26
	v_div_scale_f32 v36, vcc, s82, v39, s82
	v_fma_f32 v37, -v26, v27, 1.0
	v_fmac_f32_e32 v27, v37, v27
	v_mul_f32_e32 v37, v36, v27
	v_fma_f32 v40, -v26, v37, v36
	v_fmac_f32_e32 v37, v40, v27
	v_fma_f32 v26, -v26, v37, v36
	v_div_fmas_f32 v26, v26, v27, v37
	v_div_fixup_f32 v41, v26, v39, s82
